# phase 4 mixers: SGU row statistics with batched loads + DPP reductions, SGU tail and GLA chunk V loads issued together (on top of epilogue load hoisting)
# speedup vs baseline: 1.0072x; 1.0072x over previous
; __device__ __forceinline__ float frsq(float x) { return __builtin_amdgcn_rsqf(x); }
; __device__ __forceinline__ void sgu_unit(LAS unsigned char* lds, int b, int n, int g, const bf16_t* V, bf16_t* U, const float* ln_g, const float* ln_b, const float* w_s, const float* b_s, bool dry) {
;     ...
;     for (int rr = 0; rr < 16; ++rr) {
;         const int s = wid * 16 + rr;
;         const u32x2 raw = *(const u32x2*)(V + (size_t)(r0 + s) * 1024 + g * 256 + lane * 4);
;         const float x0 = bflo(raw.x), x1 = bfhi(raw.x), x2 = bflo(raw.y), x3 = bfhi(raw.y);
;         const float mean = wave_sum(x0 + x1 + x2 + x3) * (1.f / 256.f);
;         const float d0 = x0 - mean, d1 = x1 - mean, d2 = x2 - mean, d3 = x3 - mean;
;         const float var = wave_sum(d0 * d0 + d1 * d1 + d2 * d2 + d3 * d3) * (1.f / 256.f);
;         if (lane == 0) { st[2 * s] = mean; st[2 * s + 1] = frsq(var + EPS); }
;     }
; __global__ void __launch_bounds__(NTHREADS, 2) fwd_kernel(Args a) {
;     ...
;                 for (;;) {
;                     const int u = queue_pop(qctr + l + (dry ? 4 : 0), slot);
;                     if (u >= 1024 + 512) break;
;                     if (u < 1024) {
;                         gla_pre_unit(lds, u >> 7, (u >> 5) & 3, u & 31, ws, AIN(12) + (size_t)l * 16 * 512, AIN(13) + l * 512);
;                     } else {
;                         const int s = u - 1024, g = s & 3, n = (s >> 2) & 15, b = s >> 6;
.LBB0_307:
	s_or_b64 exec, exec, s[2:3]
	s_add_i32 s2, 0, 0x20000
	v_mov_b32_e32 v0, s2
	s_waitcnt lgkmcnt(0)
	s_barrier
	ds_read_b32 v0, v0
	s_movk_i32 s2, 0x5ff
	s_waitcnt lgkmcnt(0)
	v_cmp_lt_i32_e32 vcc, s2, v0
	v_readfirstlane_b32 s62, v0
	s_mov_b64 s[2:3], -1
	s_cbranch_vccnz .LBB0_302
	s_cmpk_gt_i32 s62, 0x3ff
	s_cbranch_scc0 .LBB0_320
	v_and_b32_e32 v0, 64, v240
	v_add_u32_e32 v0, 64, v0
	v_xor_b32_e32 v1, 1, v240
	v_cmp_lt_i32_e32 vcc, v1, v0
	v_mov_b32_e32 v2, v238
	s_lshl_b32 s2, s62, 5
	v_cndmask_b32_e32 v1, v240, v1, vcc
	v_lshlrev_b32_e32 v3, 2, v1
	v_xor_b32_e32 v1, 2, v240
	v_cmp_lt_i32_e32 vcc, v1, v0
	s_load_dwordx8 s[12:19], s[76:77], 0x38
	s_and_b32 s3, s2, 0x7ffff800
	v_cndmask_b32_e32 v1, v240, v1, vcc
	v_lshlrev_b32_e32 v4, 2, v1
	v_xor_b32_e32 v1, 4, v240
	v_cmp_lt_i32_e32 vcc, v1, v0
	s_waitcnt vmcnt(18)
	v_ashrrev_i32_e32 v55, 2, v2
	s_addk_i32 s3, 0x8000
	v_cndmask_b32_e32 v1, v240, v1, vcc
	v_lshlrev_b32_e32 v5, 2, v1
	v_xor_b32_e32 v1, 8, v240
	v_cmp_lt_i32_e32 vcc, v1, v0
	s_and_b32 s2, s2, 0x780
	s_waitcnt vmcnt(17)
	v_and_b32_e32 v56, -16, v55
	v_cndmask_b32_e32 v1, v240, v1, vcc
	v_lshlrev_b32_e32 v6, 2, v1
	v_xor_b32_e32 v1, 16, v240
	v_cmp_lt_i32_e32 vcc, v1, v0
	s_or_b32 s41, s3, s2
	v_and_b32_e32 v54, 63, v2
	v_cndmask_b32_e32 v1, v240, v1, vcc
	v_lshlrev_b32_e32 v7, 2, v1
	v_xor_b32_e32 v1, 32, v240
	v_cmp_lt_i32_e32 vcc, v1, v0
	s_and_b32 s42, s62, 3
	s_lshl_b32 s28, s42, 9
	v_cndmask_b32_e32 v0, v240, v1, vcc
	v_lshlrev_b32_e32 v8, 2, v0
	v_lshlrev_b32_e32 v0, 3, v55
	v_and_b32_e32 v0, 0xffffff80, v0
	v_add_u32_e32 v9, 0, v0
	v_add_u32_e32 v0, s41, v56
	v_ashrrev_i32_e32 v1, 31, v0
	v_lshlrev_b64 v[0:1], 11, v[0:1]
	v_lshlrev_b32_e32 v10, 3, v54
	v_or3_b32 v0, v0, s28, v10
	s_mov_b32 s4, 0
	v_cmp_eq_u32_e32 vcc, 0, v54
	v_lshl_add_u64 v[0:1], s[92:93], 0, v[0:1]
	s_waitcnt lgkmcnt(0)
	s_barrier
	s_mov_b64 s[2:3], 0x1000
	global_load_dwordx2 v[82:83], v[0:1], off
	global_load_dwordx2 v[84:85], v[0:1], off offset:2048
	v_lshl_add_u64 v[0:1], v[0:1], 0, s[2:3]
	global_load_dwordx2 v[86:87], v[0:1], off
	global_load_dwordx2 v[88:89], v[0:1], off offset:2048
	v_lshl_add_u64 v[0:1], v[0:1], 0, s[2:3]
	global_load_dwordx2 v[90:91], v[0:1], off
	global_load_dwordx2 v[92:93], v[0:1], off offset:2048
	v_lshl_add_u64 v[0:1], v[0:1], 0, s[2:3]
	global_load_dwordx2 v[94:95], v[0:1], off
	global_load_dwordx2 v[96:97], v[0:1], off offset:2048
	v_lshl_add_u64 v[0:1], v[0:1], 0, s[2:3]
	global_load_dwordx2 v[98:99], v[0:1], off
	global_load_dwordx2 v[100:101], v[0:1], off offset:2048
	v_lshl_add_u64 v[0:1], v[0:1], 0, s[2:3]
	global_load_dwordx2 v[102:103], v[0:1], off
	global_load_dwordx2 v[104:105], v[0:1], off offset:2048
	v_lshl_add_u64 v[0:1], v[0:1], 0, s[2:3]
	global_load_dwordx2 v[106:107], v[0:1], off
	global_load_dwordx2 v[108:109], v[0:1], off offset:2048
	v_lshl_add_u64 v[0:1], v[0:1], 0, s[2:3]
	global_load_dwordx2 v[110:111], v[0:1], off
	global_load_dwordx2 v[112:113], v[0:1], off offset:2048
	v_add_u32_e32 v9, 0x11000, v9
	s_waitcnt vmcnt(15)
	v_lshlrev_b32_e32 v12, 16, v82
	v_and_b32_e32 v13, 0xffff0000, v82
	v_lshlrev_b32_e32 v14, 16, v83
	v_and_b32_e32 v11, 0xffff0000, v83
	v_add_f32_e32 v10, v12, v13
	v_add_f32_e32 v10, v10, v14
	v_add_f32_e32 v10, v10, v11
	s_nop 1
	v_add_f32_dpp v10, v10, v10 quad_perm:[1,0,3,2] row_mask:0xf bank_mask:0xf
	s_nop 1
	v_add_f32_dpp v10, v10, v10 quad_perm:[2,3,0,1] row_mask:0xf bank_mask:0xf
	s_nop 1
	v_add_f32_dpp v10, v10, v10 row_half_mirror row_mask:0xf bank_mask:0xf
	s_nop 1
	v_add_f32_dpp v10, v10, v10 row_mirror row_mask:0xf bank_mask:0xf
	s_nop 1
	v_add_f32_dpp v10, v10, v10 row_bcast:15 row_mask:0xa bank_mask:0xf
	s_nop 1
	v_add_f32_dpp v10, v10, v10 row_bcast:31 row_mask:0xc bank_mask:0xf
	s_nop 1
	v_readlane_b32 s4, v10, 63
	s_nop 3
	v_mov_b32_e32 v10, s4
	v_fmac_f32_e32 v13, 0xbb800000, v10
	v_fmac_f32_e32 v12, 0xbb800000, v10
	v_mul_f32_e32 v13, v13, v13
	v_fmac_f32_e32 v14, 0xbb800000, v10
	v_fmac_f32_e32 v13, v12, v12
	v_fmac_f32_e32 v11, 0xbb800000, v10
	v_fmac_f32_e32 v13, v14, v14
	v_fmac_f32_e32 v13, v11, v11
	s_nop 1
	v_add_f32_dpp v13, v13, v13 quad_perm:[1,0,3,2] row_mask:0xf bank_mask:0xf
	s_nop 1
	v_add_f32_dpp v13, v13, v13 quad_perm:[2,3,0,1] row_mask:0xf bank_mask:0xf
	s_nop 1
	v_add_f32_dpp v13, v13, v13 row_half_mirror row_mask:0xf bank_mask:0xf
	s_nop 1
	v_add_f32_dpp v13, v13, v13 row_mirror row_mask:0xf bank_mask:0xf
	s_nop 1
	v_add_f32_dpp v13, v13, v13 row_bcast:15 row_mask:0xa bank_mask:0xf
	s_nop 1
	v_add_f32_dpp v13, v13, v13 row_bcast:31 row_mask:0xc bank_mask:0xf
	s_nop 1
	v_readlane_b32 s5, v13, 63
	s_nop 3
	v_mov_b32_e32 v11, s5
	v_fmamk_f32 v11, v11, 0x3b800000, v239
	v_rsq_f32_e32 v11, v11
	v_mul_f32_e32 v10, 0x3b800000, v10
	s_and_saveexec_b64 s[2:3], vcc
	s_nop 0
	ds_write_b64 v9, v[10:11] offset:0
	s_or_b64 exec, exec, s[2:3]
	s_waitcnt vmcnt(14)
; __device__ __forceinline__ float frsq(float x) { return __builtin_amdgcn_rsqf(x); }
; __device__ __forceinline__ float wave_sum(float v) {
; #pragma unroll
;     for (int d = 1; d < 64; d <<= 1) v += __shfl_xor(v, d);
;     return v;
; }
; __device__ __forceinline__ void sgu_unit(LAS unsigned char* lds, int b, int n, int g, const bf16_t* V, bf16_t* U, const float* ln_g, const float* ln_b, const float* w_s, const float* b_s, bool dry) {
;     ...
;     for (int rr = 0; rr < 16; ++rr) {
;         const int s = wid * 16 + rr;
;         const u32x2 raw = *(const u32x2*)(V + (size_t)(r0 + s) * 1024 + g * 256 + lane * 4);
;         const float x0 = bflo(raw.x), x1 = bfhi(raw.x), x2 = bflo(raw.y), x3 = bfhi(raw.y);
;         const float mean = wave_sum(x0 + x1 + x2 + x3) * (1.f / 256.f);
;         const float d0 = x0 - mean, d1 = x1 - mean, d2 = x2 - mean, d3 = x3 - mean;
;         const float var = wave_sum(d0 * d0 + d1 * d1 + d2 * d2 + d3 * d3) * (1.f / 256.f);
;         if (lane == 0) { st[2 * s] = mean; st[2 * s + 1] = frsq(var + EPS); }
;     }
	v_lshlrev_b32_e32 v12, 16, v84
	v_and_b32_e32 v13, 0xffff0000, v84
	v_lshlrev_b32_e32 v14, 16, v85
	v_and_b32_e32 v11, 0xffff0000, v85
	v_add_f32_e32 v10, v12, v13
	v_add_f32_e32 v10, v10, v14
	v_add_f32_e32 v10, v10, v11
	s_nop 1
	v_add_f32_dpp v10, v10, v10 quad_perm:[1,0,3,2] row_mask:0xf bank_mask:0xf
	s_nop 1
	v_add_f32_dpp v10, v10, v10 quad_perm:[2,3,0,1] row_mask:0xf bank_mask:0xf
	s_nop 1
	v_add_f32_dpp v10, v10, v10 row_half_mirror row_mask:0xf bank_mask:0xf
	s_nop 1
	v_add_f32_dpp v10, v10, v10 row_mirror row_mask:0xf bank_mask:0xf
	s_nop 1
	v_add_f32_dpp v10, v10, v10 row_bcast:15 row_mask:0xa bank_mask:0xf
	s_nop 1
	v_add_f32_dpp v10, v10, v10 row_bcast:31 row_mask:0xc bank_mask:0xf
	s_nop 1
	v_readlane_b32 s4, v10, 63
	s_nop 3
	v_mov_b32_e32 v10, s4
	v_fmac_f32_e32 v13, 0xbb800000, v10
	v_fmac_f32_e32 v12, 0xbb800000, v10
	v_mul_f32_e32 v13, v13, v13
	v_fmac_f32_e32 v14, 0xbb800000, v10
	v_fmac_f32_e32 v13, v12, v12
	v_fmac_f32_e32 v11, 0xbb800000, v10
	v_fmac_f32_e32 v13, v14, v14
	v_fmac_f32_e32 v13, v11, v11
	s_nop 1
	v_add_f32_dpp v13, v13, v13 quad_perm:[1,0,3,2] row_mask:0xf bank_mask:0xf
	s_nop 1
	v_add_f32_dpp v13, v13, v13 quad_perm:[2,3,0,1] row_mask:0xf bank_mask:0xf
	s_nop 1
	v_add_f32_dpp v13, v13, v13 row_half_mirror row_mask:0xf bank_mask:0xf
	s_nop 1
	v_add_f32_dpp v13, v13, v13 row_mirror row_mask:0xf bank_mask:0xf
	s_nop 1
	v_add_f32_dpp v13, v13, v13 row_bcast:15 row_mask:0xa bank_mask:0xf
	s_nop 1
	v_add_f32_dpp v13, v13, v13 row_bcast:31 row_mask:0xc bank_mask:0xf
	s_nop 1
	v_readlane_b32 s5, v13, 63
	s_nop 3
	v_mov_b32_e32 v11, s5
	v_fmamk_f32 v11, v11, 0x3b800000, v239
	v_rsq_f32_e32 v11, v11
	v_mul_f32_e32 v10, 0x3b800000, v10
	s_and_saveexec_b64 s[2:3], vcc
	s_nop 0
	ds_write_b64 v9, v[10:11] offset:8
	s_or_b64 exec, exec, s[2:3]
	s_waitcnt vmcnt(13)
	v_lshlrev_b32_e32 v12, 16, v86
	v_and_b32_e32 v13, 0xffff0000, v86
	v_lshlrev_b32_e32 v14, 16, v87
	v_and_b32_e32 v11, 0xffff0000, v87
	v_add_f32_e32 v10, v12, v13
	v_add_f32_e32 v10, v10, v14
	v_add_f32_e32 v10, v10, v11
	s_nop 1
	v_add_f32_dpp v10, v10, v10 quad_perm:[1,0,3,2] row_mask:0xf bank_mask:0xf
	s_nop 1
	v_add_f32_dpp v10, v10, v10 quad_perm:[2,3,0,1] row_mask:0xf bank_mask:0xf
	s_nop 1
	v_add_f32_dpp v10, v10, v10 row_half_mirror row_mask:0xf bank_mask:0xf
	s_nop 1
	v_add_f32_dpp v10, v10, v10 row_mirror row_mask:0xf bank_mask:0xf
	s_nop 1
	v_add_f32_dpp v10, v10, v10 row_bcast:15 row_mask:0xa bank_mask:0xf
	s_nop 1
	v_add_f32_dpp v10, v10, v10 row_bcast:31 row_mask:0xc bank_mask:0xf
	s_nop 1
	v_readlane_b32 s4, v10, 63
	s_nop 3
	v_mov_b32_e32 v10, s4
	v_fmac_f32_e32 v13, 0xbb800000, v10
	v_fmac_f32_e32 v12, 0xbb800000, v10
	v_mul_f32_e32 v13, v13, v13
	v_fmac_f32_e32 v14, 0xbb800000, v10
	v_fmac_f32_e32 v13, v12, v12
	v_fmac_f32_e32 v11, 0xbb800000, v10
	v_fmac_f32_e32 v13, v14, v14
	v_fmac_f32_e32 v13, v11, v11
	s_nop 1
	v_add_f32_dpp v13, v13, v13 quad_perm:[1,0,3,2] row_mask:0xf bank_mask:0xf
	s_nop 1
	v_add_f32_dpp v13, v13, v13 quad_perm:[2,3,0,1] row_mask:0xf bank_mask:0xf
	s_nop 1
	v_add_f32_dpp v13, v13, v13 row_half_mirror row_mask:0xf bank_mask:0xf
	s_nop 1
	v_add_f32_dpp v13, v13, v13 row_mirror row_mask:0xf bank_mask:0xf
	s_nop 1
	v_add_f32_dpp v13, v13, v13 row_bcast:15 row_mask:0xa bank_mask:0xf
	s_nop 1
	v_add_f32_dpp v13, v13, v13 row_bcast:31 row_mask:0xc bank_mask:0xf
	s_nop 1
	v_readlane_b32 s5, v13, 63
	s_nop 3
	v_mov_b32_e32 v11, s5
	v_fmamk_f32 v11, v11, 0x3b800000, v239
	v_rsq_f32_e32 v11, v11
	v_mul_f32_e32 v10, 0x3b800000, v10
	s_and_saveexec_b64 s[2:3], vcc
	s_nop 0
	ds_write_b64 v9, v[10:11] offset:16
	s_or_b64 exec, exec, s[2:3]
	s_waitcnt vmcnt(12)
	v_lshlrev_b32_e32 v12, 16, v88
	v_and_b32_e32 v13, 0xffff0000, v88
	v_lshlrev_b32_e32 v14, 16, v89
	v_and_b32_e32 v11, 0xffff0000, v89
	v_add_f32_e32 v10, v12, v13
	v_add_f32_e32 v10, v10, v14
	v_add_f32_e32 v10, v10, v11
	s_nop 1
	v_add_f32_dpp v10, v10, v10 quad_perm:[1,0,3,2] row_mask:0xf bank_mask:0xf
	s_nop 1
	v_add_f32_dpp v10, v10, v10 quad_perm:[2,3,0,1] row_mask:0xf bank_mask:0xf
	s_nop 1
	v_add_f32_dpp v10, v10, v10 row_half_mirror row_mask:0xf bank_mask:0xf
	s_nop 1
	v_add_f32_dpp v10, v10, v10 row_mirror row_mask:0xf bank_mask:0xf
	s_nop 1
	v_add_f32_dpp v10, v10, v10 row_bcast:15 row_mask:0xa bank_mask:0xf
	s_nop 1
	v_add_f32_dpp v10, v10, v10 row_bcast:31 row_mask:0xc bank_mask:0xf
	s_nop 1
	v_readlane_b32 s4, v10, 63
	s_nop 3
	v_mov_b32_e32 v10, s4
	v_fmac_f32_e32 v13, 0xbb800000, v10
	v_fmac_f32_e32 v12, 0xbb800000, v10
	v_mul_f32_e32 v13, v13, v13
	v_fmac_f32_e32 v14, 0xbb800000, v10
	v_fmac_f32_e32 v13, v12, v12
	v_fmac_f32_e32 v11, 0xbb800000, v10
	v_fmac_f32_e32 v13, v14, v14
	v_fmac_f32_e32 v13, v11, v11
	s_nop 1
	v_add_f32_dpp v13, v13, v13 quad_perm:[1,0,3,2] row_mask:0xf bank_mask:0xf
	s_nop 1
	v_add_f32_dpp v13, v13, v13 quad_perm:[2,3,0,1] row_mask:0xf bank_mask:0xf
	s_nop 1
	v_add_f32_dpp v13, v13, v13 row_half_mirror row_mask:0xf bank_mask:0xf
	s_nop 1
	v_add_f32_dpp v13, v13, v13 row_mirror row_mask:0xf bank_mask:0xf
	s_nop 1
	v_add_f32_dpp v13, v13, v13 row_bcast:15 row_mask:0xa bank_mask:0xf
	s_nop 1
	v_add_f32_dpp v13, v13, v13 row_bcast:31 row_mask:0xc bank_mask:0xf
	s_nop 1
	v_readlane_b32 s5, v13, 63
	s_nop 3
	v_mov_b32_e32 v11, s5
	v_fmamk_f32 v11, v11, 0x3b800000, v239
	v_rsq_f32_e32 v11, v11
	v_mul_f32_e32 v10, 0x3b800000, v10
	s_and_saveexec_b64 s[2:3], vcc
	s_nop 0
	ds_write_b64 v9, v[10:11] offset:24
	s_or_b64 exec, exec, s[2:3]
	s_waitcnt vmcnt(11)
; __device__ __forceinline__ float frsq(float x) { return __builtin_amdgcn_rsqf(x); }
; __device__ __forceinline__ float wave_sum(float v) {
; #pragma unroll
;     for (int d = 1; d < 64; d <<= 1) v += __shfl_xor(v, d);
;     return v;
; }
; __device__ __forceinline__ void sgu_unit(LAS unsigned char* lds, int b, int n, int g, const bf16_t* V, bf16_t* U, const float* ln_g, const float* ln_b, const float* w_s, const float* b_s, bool dry) {
;     ...
;     for (int rr = 0; rr < 16; ++rr) {
;         const int s = wid * 16 + rr;
;         const u32x2 raw = *(const u32x2*)(V + (size_t)(r0 + s) * 1024 + g * 256 + lane * 4);
;         const float x0 = bflo(raw.x), x1 = bfhi(raw.x), x2 = bflo(raw.y), x3 = bfhi(raw.y);
;         const float mean = wave_sum(x0 + x1 + x2 + x3) * (1.f / 256.f);
;         const float d0 = x0 - mean, d1 = x1 - mean, d2 = x2 - mean, d3 = x3 - mean;
;         const float var = wave_sum(d0 * d0 + d1 * d1 + d2 * d2 + d3 * d3) * (1.f / 256.f);
;         if (lane == 0) { st[2 * s] = mean; st[2 * s + 1] = frsq(var + EPS); }
;     }
	v_lshlrev_b32_e32 v12, 16, v90
	v_and_b32_e32 v13, 0xffff0000, v90
	v_lshlrev_b32_e32 v14, 16, v91
	v_and_b32_e32 v11, 0xffff0000, v91
	v_add_f32_e32 v10, v12, v13
	v_add_f32_e32 v10, v10, v14
	v_add_f32_e32 v10, v10, v11
	s_nop 1
	v_add_f32_dpp v10, v10, v10 quad_perm:[1,0,3,2] row_mask:0xf bank_mask:0xf
	s_nop 1
	v_add_f32_dpp v10, v10, v10 quad_perm:[2,3,0,1] row_mask:0xf bank_mask:0xf
	s_nop 1
	v_add_f32_dpp v10, v10, v10 row_half_mirror row_mask:0xf bank_mask:0xf
	s_nop 1
	v_add_f32_dpp v10, v10, v10 row_mirror row_mask:0xf bank_mask:0xf
	s_nop 1
	v_add_f32_dpp v10, v10, v10 row_bcast:15 row_mask:0xa bank_mask:0xf
	s_nop 1
	v_add_f32_dpp v10, v10, v10 row_bcast:31 row_mask:0xc bank_mask:0xf
	s_nop 1
	v_readlane_b32 s4, v10, 63
	s_nop 3
	v_mov_b32_e32 v10, s4
	v_fmac_f32_e32 v13, 0xbb800000, v10
	v_fmac_f32_e32 v12, 0xbb800000, v10
	v_mul_f32_e32 v13, v13, v13
	v_fmac_f32_e32 v14, 0xbb800000, v10
	v_fmac_f32_e32 v13, v12, v12
	v_fmac_f32_e32 v11, 0xbb800000, v10
	v_fmac_f32_e32 v13, v14, v14
	v_fmac_f32_e32 v13, v11, v11
	s_nop 1
	v_add_f32_dpp v13, v13, v13 quad_perm:[1,0,3,2] row_mask:0xf bank_mask:0xf
	s_nop 1
	v_add_f32_dpp v13, v13, v13 quad_perm:[2,3,0,1] row_mask:0xf bank_mask:0xf
	s_nop 1
	v_add_f32_dpp v13, v13, v13 row_half_mirror row_mask:0xf bank_mask:0xf
	s_nop 1
	v_add_f32_dpp v13, v13, v13 row_mirror row_mask:0xf bank_mask:0xf
	s_nop 1
	v_add_f32_dpp v13, v13, v13 row_bcast:15 row_mask:0xa bank_mask:0xf
	s_nop 1
	v_add_f32_dpp v13, v13, v13 row_bcast:31 row_mask:0xc bank_mask:0xf
	s_nop 1
	v_readlane_b32 s5, v13, 63
	s_nop 3
	v_mov_b32_e32 v11, s5
	v_fmamk_f32 v11, v11, 0x3b800000, v239
	v_rsq_f32_e32 v11, v11
	v_mul_f32_e32 v10, 0x3b800000, v10
	s_and_saveexec_b64 s[2:3], vcc
	s_nop 0
	ds_write_b64 v9, v[10:11] offset:32
	s_or_b64 exec, exec, s[2:3]
	s_waitcnt vmcnt(10)
	v_lshlrev_b32_e32 v12, 16, v92
	v_and_b32_e32 v13, 0xffff0000, v92
	v_lshlrev_b32_e32 v14, 16, v93
	v_and_b32_e32 v11, 0xffff0000, v93
	v_add_f32_e32 v10, v12, v13
	v_add_f32_e32 v10, v10, v14
	v_add_f32_e32 v10, v10, v11
	s_nop 1
	v_add_f32_dpp v10, v10, v10 quad_perm:[1,0,3,2] row_mask:0xf bank_mask:0xf
	s_nop 1
	v_add_f32_dpp v10, v10, v10 quad_perm:[2,3,0,1] row_mask:0xf bank_mask:0xf
	s_nop 1
	v_add_f32_dpp v10, v10, v10 row_half_mirror row_mask:0xf bank_mask:0xf
	s_nop 1
	v_add_f32_dpp v10, v10, v10 row_mirror row_mask:0xf bank_mask:0xf
	s_nop 1
	v_add_f32_dpp v10, v10, v10 row_bcast:15 row_mask:0xa bank_mask:0xf
	s_nop 1
	v_add_f32_dpp v10, v10, v10 row_bcast:31 row_mask:0xc bank_mask:0xf
	s_nop 1
	v_readlane_b32 s4, v10, 63
	s_nop 3
	v_mov_b32_e32 v10, s4
	v_fmac_f32_e32 v13, 0xbb800000, v10
	v_fmac_f32_e32 v12, 0xbb800000, v10
	v_mul_f32_e32 v13, v13, v13
	v_fmac_f32_e32 v14, 0xbb800000, v10
	v_fmac_f32_e32 v13, v12, v12
	v_fmac_f32_e32 v11, 0xbb800000, v10
	v_fmac_f32_e32 v13, v14, v14
	v_fmac_f32_e32 v13, v11, v11
	s_nop 1
	v_add_f32_dpp v13, v13, v13 quad_perm:[1,0,3,2] row_mask:0xf bank_mask:0xf
	s_nop 1
	v_add_f32_dpp v13, v13, v13 quad_perm:[2,3,0,1] row_mask:0xf bank_mask:0xf
	s_nop 1
	v_add_f32_dpp v13, v13, v13 row_half_mirror row_mask:0xf bank_mask:0xf
	s_nop 1
	v_add_f32_dpp v13, v13, v13 row_mirror row_mask:0xf bank_mask:0xf
	s_nop 1
	v_add_f32_dpp v13, v13, v13 row_bcast:15 row_mask:0xa bank_mask:0xf
	s_nop 1
	v_add_f32_dpp v13, v13, v13 row_bcast:31 row_mask:0xc bank_mask:0xf
	s_nop 1
	v_readlane_b32 s5, v13, 63
	s_nop 3
	v_mov_b32_e32 v11, s5
	v_fmamk_f32 v11, v11, 0x3b800000, v239
	v_rsq_f32_e32 v11, v11
	v_mul_f32_e32 v10, 0x3b800000, v10
	s_and_saveexec_b64 s[2:3], vcc
	s_nop 0
	ds_write_b64 v9, v[10:11] offset:40
	s_or_b64 exec, exec, s[2:3]
	s_waitcnt vmcnt(9)
	v_lshlrev_b32_e32 v12, 16, v94
	v_and_b32_e32 v13, 0xffff0000, v94
	v_lshlrev_b32_e32 v14, 16, v95
	v_and_b32_e32 v11, 0xffff0000, v95
	v_add_f32_e32 v10, v12, v13
	v_add_f32_e32 v10, v10, v14
	v_add_f32_e32 v10, v10, v11
	s_nop 1
	v_add_f32_dpp v10, v10, v10 quad_perm:[1,0,3,2] row_mask:0xf bank_mask:0xf
	s_nop 1
	v_add_f32_dpp v10, v10, v10 quad_perm:[2,3,0,1] row_mask:0xf bank_mask:0xf
	s_nop 1
	v_add_f32_dpp v10, v10, v10 row_half_mirror row_mask:0xf bank_mask:0xf
	s_nop 1
	v_add_f32_dpp v10, v10, v10 row_mirror row_mask:0xf bank_mask:0xf
	s_nop 1
	v_add_f32_dpp v10, v10, v10 row_bcast:15 row_mask:0xa bank_mask:0xf
	s_nop 1
	v_add_f32_dpp v10, v10, v10 row_bcast:31 row_mask:0xc bank_mask:0xf
	s_nop 1
	v_readlane_b32 s4, v10, 63
	s_nop 3
	v_mov_b32_e32 v10, s4
	v_fmac_f32_e32 v13, 0xbb800000, v10
	v_fmac_f32_e32 v12, 0xbb800000, v10
	v_mul_f32_e32 v13, v13, v13
	v_fmac_f32_e32 v14, 0xbb800000, v10
	v_fmac_f32_e32 v13, v12, v12
	v_fmac_f32_e32 v11, 0xbb800000, v10
	v_fmac_f32_e32 v13, v14, v14
	v_fmac_f32_e32 v13, v11, v11
	s_nop 1
	v_add_f32_dpp v13, v13, v13 quad_perm:[1,0,3,2] row_mask:0xf bank_mask:0xf
	s_nop 1
	v_add_f32_dpp v13, v13, v13 quad_perm:[2,3,0,1] row_mask:0xf bank_mask:0xf
	s_nop 1
	v_add_f32_dpp v13, v13, v13 row_half_mirror row_mask:0xf bank_mask:0xf
	s_nop 1
	v_add_f32_dpp v13, v13, v13 row_mirror row_mask:0xf bank_mask:0xf
	s_nop 1
	v_add_f32_dpp v13, v13, v13 row_bcast:15 row_mask:0xa bank_mask:0xf
	s_nop 1
	v_add_f32_dpp v13, v13, v13 row_bcast:31 row_mask:0xc bank_mask:0xf
	s_nop 1
	v_readlane_b32 s5, v13, 63
	s_nop 3
	v_mov_b32_e32 v11, s5
	v_fmamk_f32 v11, v11, 0x3b800000, v239
	v_rsq_f32_e32 v11, v11
	v_mul_f32_e32 v10, 0x3b800000, v10
	s_and_saveexec_b64 s[2:3], vcc
	s_nop 0
	ds_write_b64 v9, v[10:11] offset:48
	s_or_b64 exec, exec, s[2:3]
	s_waitcnt vmcnt(8)
; __device__ __forceinline__ float frsq(float x) { return __builtin_amdgcn_rsqf(x); }
; __device__ __forceinline__ float wave_sum(float v) {
; #pragma unroll
;     for (int d = 1; d < 64; d <<= 1) v += __shfl_xor(v, d);
;     return v;
; }
; __device__ __forceinline__ void sgu_unit(LAS unsigned char* lds, int b, int n, int g, const bf16_t* V, bf16_t* U, const float* ln_g, const float* ln_b, const float* w_s, const float* b_s, bool dry) {
;     ...
;     for (int rr = 0; rr < 16; ++rr) {
;         const int s = wid * 16 + rr;
;         const u32x2 raw = *(const u32x2*)(V + (size_t)(r0 + s) * 1024 + g * 256 + lane * 4);
;         const float x0 = bflo(raw.x), x1 = bfhi(raw.x), x2 = bflo(raw.y), x3 = bfhi(raw.y);
;         const float mean = wave_sum(x0 + x1 + x2 + x3) * (1.f / 256.f);
;         const float d0 = x0 - mean, d1 = x1 - mean, d2 = x2 - mean, d3 = x3 - mean;
;         const float var = wave_sum(d0 * d0 + d1 * d1 + d2 * d2 + d3 * d3) * (1.f / 256.f);
;         if (lane == 0) { st[2 * s] = mean; st[2 * s + 1] = frsq(var + EPS); }
;     }
	v_lshlrev_b32_e32 v12, 16, v96
	v_and_b32_e32 v13, 0xffff0000, v96
	v_lshlrev_b32_e32 v14, 16, v97
	v_and_b32_e32 v11, 0xffff0000, v97
	v_add_f32_e32 v10, v12, v13
	v_add_f32_e32 v10, v10, v14
	v_add_f32_e32 v10, v10, v11
	s_nop 1
	v_add_f32_dpp v10, v10, v10 quad_perm:[1,0,3,2] row_mask:0xf bank_mask:0xf
	s_nop 1
	v_add_f32_dpp v10, v10, v10 quad_perm:[2,3,0,1] row_mask:0xf bank_mask:0xf
	s_nop 1
	v_add_f32_dpp v10, v10, v10 row_half_mirror row_mask:0xf bank_mask:0xf
	s_nop 1
	v_add_f32_dpp v10, v10, v10 row_mirror row_mask:0xf bank_mask:0xf
	s_nop 1
	v_add_f32_dpp v10, v10, v10 row_bcast:15 row_mask:0xa bank_mask:0xf
	s_nop 1
	v_add_f32_dpp v10, v10, v10 row_bcast:31 row_mask:0xc bank_mask:0xf
	s_nop 1
	v_readlane_b32 s4, v10, 63
	s_nop 3
	v_mov_b32_e32 v10, s4
	v_fmac_f32_e32 v13, 0xbb800000, v10
	v_fmac_f32_e32 v12, 0xbb800000, v10
	v_mul_f32_e32 v13, v13, v13
	v_fmac_f32_e32 v14, 0xbb800000, v10
	v_fmac_f32_e32 v13, v12, v12
	v_fmac_f32_e32 v11, 0xbb800000, v10
	v_fmac_f32_e32 v13, v14, v14
	v_fmac_f32_e32 v13, v11, v11
	s_nop 1
	v_add_f32_dpp v13, v13, v13 quad_perm:[1,0,3,2] row_mask:0xf bank_mask:0xf
	s_nop 1
	v_add_f32_dpp v13, v13, v13 quad_perm:[2,3,0,1] row_mask:0xf bank_mask:0xf
	s_nop 1
	v_add_f32_dpp v13, v13, v13 row_half_mirror row_mask:0xf bank_mask:0xf
	s_nop 1
	v_add_f32_dpp v13, v13, v13 row_mirror row_mask:0xf bank_mask:0xf
	s_nop 1
	v_add_f32_dpp v13, v13, v13 row_bcast:15 row_mask:0xa bank_mask:0xf
	s_nop 1
	v_add_f32_dpp v13, v13, v13 row_bcast:31 row_mask:0xc bank_mask:0xf
	s_nop 1
	v_readlane_b32 s5, v13, 63
	s_nop 3
	v_mov_b32_e32 v11, s5
	v_fmamk_f32 v11, v11, 0x3b800000, v239
	v_rsq_f32_e32 v11, v11
	v_mul_f32_e32 v10, 0x3b800000, v10
	s_and_saveexec_b64 s[2:3], vcc
	s_nop 0
	ds_write_b64 v9, v[10:11] offset:56
	s_or_b64 exec, exec, s[2:3]
	s_waitcnt vmcnt(7)
	v_lshlrev_b32_e32 v12, 16, v98
	v_and_b32_e32 v13, 0xffff0000, v98
	v_lshlrev_b32_e32 v14, 16, v99
	v_and_b32_e32 v11, 0xffff0000, v99
	v_add_f32_e32 v10, v12, v13
	v_add_f32_e32 v10, v10, v14
	v_add_f32_e32 v10, v10, v11
	s_nop 1
	v_add_f32_dpp v10, v10, v10 quad_perm:[1,0,3,2] row_mask:0xf bank_mask:0xf
	s_nop 1
	v_add_f32_dpp v10, v10, v10 quad_perm:[2,3,0,1] row_mask:0xf bank_mask:0xf
	s_nop 1
	v_add_f32_dpp v10, v10, v10 row_half_mirror row_mask:0xf bank_mask:0xf
	s_nop 1
	v_add_f32_dpp v10, v10, v10 row_mirror row_mask:0xf bank_mask:0xf
	s_nop 1
	v_add_f32_dpp v10, v10, v10 row_bcast:15 row_mask:0xa bank_mask:0xf
	s_nop 1
	v_add_f32_dpp v10, v10, v10 row_bcast:31 row_mask:0xc bank_mask:0xf
	s_nop 1
	v_readlane_b32 s4, v10, 63
	s_nop 3
	v_mov_b32_e32 v10, s4
	v_fmac_f32_e32 v13, 0xbb800000, v10
	v_fmac_f32_e32 v12, 0xbb800000, v10
	v_mul_f32_e32 v13, v13, v13
	v_fmac_f32_e32 v14, 0xbb800000, v10
	v_fmac_f32_e32 v13, v12, v12
	v_fmac_f32_e32 v11, 0xbb800000, v10
	v_fmac_f32_e32 v13, v14, v14
	v_fmac_f32_e32 v13, v11, v11
	s_nop 1
	v_add_f32_dpp v13, v13, v13 quad_perm:[1,0,3,2] row_mask:0xf bank_mask:0xf
	s_nop 1
	v_add_f32_dpp v13, v13, v13 quad_perm:[2,3,0,1] row_mask:0xf bank_mask:0xf
	s_nop 1
	v_add_f32_dpp v13, v13, v13 row_half_mirror row_mask:0xf bank_mask:0xf
	s_nop 1
	v_add_f32_dpp v13, v13, v13 row_mirror row_mask:0xf bank_mask:0xf
	s_nop 1
	v_add_f32_dpp v13, v13, v13 row_bcast:15 row_mask:0xa bank_mask:0xf
	s_nop 1
	v_add_f32_dpp v13, v13, v13 row_bcast:31 row_mask:0xc bank_mask:0xf
	s_nop 1
	v_readlane_b32 s5, v13, 63
	s_nop 3
	v_mov_b32_e32 v11, s5
	v_fmamk_f32 v11, v11, 0x3b800000, v239
	v_rsq_f32_e32 v11, v11
	v_mul_f32_e32 v10, 0x3b800000, v10
	s_and_saveexec_b64 s[2:3], vcc
	s_nop 0
	ds_write_b64 v9, v[10:11] offset:64
	s_or_b64 exec, exec, s[2:3]
	s_waitcnt vmcnt(6)
	v_lshlrev_b32_e32 v12, 16, v100
	v_and_b32_e32 v13, 0xffff0000, v100
	v_lshlrev_b32_e32 v14, 16, v101
	v_and_b32_e32 v11, 0xffff0000, v101
	v_add_f32_e32 v10, v12, v13
	v_add_f32_e32 v10, v10, v14
	v_add_f32_e32 v10, v10, v11
	s_nop 1
	v_add_f32_dpp v10, v10, v10 quad_perm:[1,0,3,2] row_mask:0xf bank_mask:0xf
	s_nop 1
	v_add_f32_dpp v10, v10, v10 quad_perm:[2,3,0,1] row_mask:0xf bank_mask:0xf
	s_nop 1
	v_add_f32_dpp v10, v10, v10 row_half_mirror row_mask:0xf bank_mask:0xf
	s_nop 1
	v_add_f32_dpp v10, v10, v10 row_mirror row_mask:0xf bank_mask:0xf
	s_nop 1
	v_add_f32_dpp v10, v10, v10 row_bcast:15 row_mask:0xa bank_mask:0xf
	s_nop 1
	v_add_f32_dpp v10, v10, v10 row_bcast:31 row_mask:0xc bank_mask:0xf
	s_nop 1
	v_readlane_b32 s4, v10, 63
	s_nop 3
	v_mov_b32_e32 v10, s4
	v_fmac_f32_e32 v13, 0xbb800000, v10
	v_fmac_f32_e32 v12, 0xbb800000, v10
	v_mul_f32_e32 v13, v13, v13
	v_fmac_f32_e32 v14, 0xbb800000, v10
	v_fmac_f32_e32 v13, v12, v12
	v_fmac_f32_e32 v11, 0xbb800000, v10
	v_fmac_f32_e32 v13, v14, v14
	v_fmac_f32_e32 v13, v11, v11
	s_nop 1
	v_add_f32_dpp v13, v13, v13 quad_perm:[1,0,3,2] row_mask:0xf bank_mask:0xf
	s_nop 1
	v_add_f32_dpp v13, v13, v13 quad_perm:[2,3,0,1] row_mask:0xf bank_mask:0xf
	s_nop 1
	v_add_f32_dpp v13, v13, v13 row_half_mirror row_mask:0xf bank_mask:0xf
	s_nop 1
	v_add_f32_dpp v13, v13, v13 row_mirror row_mask:0xf bank_mask:0xf
	s_nop 1
	v_add_f32_dpp v13, v13, v13 row_bcast:15 row_mask:0xa bank_mask:0xf
	s_nop 1
	v_add_f32_dpp v13, v13, v13 row_bcast:31 row_mask:0xc bank_mask:0xf
	s_nop 1
	v_readlane_b32 s5, v13, 63
	s_nop 3
	v_mov_b32_e32 v11, s5
	v_fmamk_f32 v11, v11, 0x3b800000, v239
	v_rsq_f32_e32 v11, v11
	v_mul_f32_e32 v10, 0x3b800000, v10
	s_and_saveexec_b64 s[2:3], vcc
	s_nop 0
	ds_write_b64 v9, v[10:11] offset:72
	s_or_b64 exec, exec, s[2:3]
	s_waitcnt vmcnt(5)
; __device__ __forceinline__ float frsq(float x) { return __builtin_amdgcn_rsqf(x); }
; __device__ __forceinline__ float wave_sum(float v) {
; #pragma unroll
;     for (int d = 1; d < 64; d <<= 1) v += __shfl_xor(v, d);
;     return v;
; }
; __device__ __forceinline__ void sgu_unit(LAS unsigned char* lds, int b, int n, int g, const bf16_t* V, bf16_t* U, const float* ln_g, const float* ln_b, const float* w_s, const float* b_s, bool dry) {
;     ...
;     for (int rr = 0; rr < 16; ++rr) {
;         const int s = wid * 16 + rr;
;         const u32x2 raw = *(const u32x2*)(V + (size_t)(r0 + s) * 1024 + g * 256 + lane * 4);
;         const float x0 = bflo(raw.x), x1 = bfhi(raw.x), x2 = bflo(raw.y), x3 = bfhi(raw.y);
;         const float mean = wave_sum(x0 + x1 + x2 + x3) * (1.f / 256.f);
;         const float d0 = x0 - mean, d1 = x1 - mean, d2 = x2 - mean, d3 = x3 - mean;
;         const float var = wave_sum(d0 * d0 + d1 * d1 + d2 * d2 + d3 * d3) * (1.f / 256.f);
;         if (lane == 0) { st[2 * s] = mean; st[2 * s + 1] = frsq(var + EPS); }
;     }
	v_lshlrev_b32_e32 v12, 16, v102
	v_and_b32_e32 v13, 0xffff0000, v102
	v_lshlrev_b32_e32 v14, 16, v103
	v_and_b32_e32 v11, 0xffff0000, v103
	v_add_f32_e32 v10, v12, v13
	v_add_f32_e32 v10, v10, v14
	v_add_f32_e32 v10, v10, v11
	s_nop 1
	v_add_f32_dpp v10, v10, v10 quad_perm:[1,0,3,2] row_mask:0xf bank_mask:0xf
	s_nop 1
	v_add_f32_dpp v10, v10, v10 quad_perm:[2,3,0,1] row_mask:0xf bank_mask:0xf
	s_nop 1
	v_add_f32_dpp v10, v10, v10 row_half_mirror row_mask:0xf bank_mask:0xf
	s_nop 1
	v_add_f32_dpp v10, v10, v10 row_mirror row_mask:0xf bank_mask:0xf
	s_nop 1
	v_add_f32_dpp v10, v10, v10 row_bcast:15 row_mask:0xa bank_mask:0xf
	s_nop 1
	v_add_f32_dpp v10, v10, v10 row_bcast:31 row_mask:0xc bank_mask:0xf
	s_nop 1
	v_readlane_b32 s4, v10, 63
	s_nop 3
	v_mov_b32_e32 v10, s4
	v_fmac_f32_e32 v13, 0xbb800000, v10
	v_fmac_f32_e32 v12, 0xbb800000, v10
	v_mul_f32_e32 v13, v13, v13
	v_fmac_f32_e32 v14, 0xbb800000, v10
	v_fmac_f32_e32 v13, v12, v12
	v_fmac_f32_e32 v11, 0xbb800000, v10
	v_fmac_f32_e32 v13, v14, v14
	v_fmac_f32_e32 v13, v11, v11
	s_nop 1
	v_add_f32_dpp v13, v13, v13 quad_perm:[1,0,3,2] row_mask:0xf bank_mask:0xf
	s_nop 1
	v_add_f32_dpp v13, v13, v13 quad_perm:[2,3,0,1] row_mask:0xf bank_mask:0xf
	s_nop 1
	v_add_f32_dpp v13, v13, v13 row_half_mirror row_mask:0xf bank_mask:0xf
	s_nop 1
	v_add_f32_dpp v13, v13, v13 row_mirror row_mask:0xf bank_mask:0xf
	s_nop 1
	v_add_f32_dpp v13, v13, v13 row_bcast:15 row_mask:0xa bank_mask:0xf
	s_nop 1
	v_add_f32_dpp v13, v13, v13 row_bcast:31 row_mask:0xc bank_mask:0xf
	s_nop 1
	v_readlane_b32 s5, v13, 63
	s_nop 3
	v_mov_b32_e32 v11, s5
	v_fmamk_f32 v11, v11, 0x3b800000, v239
	v_rsq_f32_e32 v11, v11
	v_mul_f32_e32 v10, 0x3b800000, v10
	s_and_saveexec_b64 s[2:3], vcc
	s_nop 0
	ds_write_b64 v9, v[10:11] offset:80
	s_or_b64 exec, exec, s[2:3]
	s_waitcnt vmcnt(4)
	v_lshlrev_b32_e32 v12, 16, v104
	v_and_b32_e32 v13, 0xffff0000, v104
	v_lshlrev_b32_e32 v14, 16, v105
	v_and_b32_e32 v11, 0xffff0000, v105
	v_add_f32_e32 v10, v12, v13
	v_add_f32_e32 v10, v10, v14
	v_add_f32_e32 v10, v10, v11
	s_nop 1
	v_add_f32_dpp v10, v10, v10 quad_perm:[1,0,3,2] row_mask:0xf bank_mask:0xf
	s_nop 1
	v_add_f32_dpp v10, v10, v10 quad_perm:[2,3,0,1] row_mask:0xf bank_mask:0xf
	s_nop 1
	v_add_f32_dpp v10, v10, v10 row_half_mirror row_mask:0xf bank_mask:0xf
	s_nop 1
	v_add_f32_dpp v10, v10, v10 row_mirror row_mask:0xf bank_mask:0xf
	s_nop 1
	v_add_f32_dpp v10, v10, v10 row_bcast:15 row_mask:0xa bank_mask:0xf
	s_nop 1
	v_add_f32_dpp v10, v10, v10 row_bcast:31 row_mask:0xc bank_mask:0xf
	s_nop 1
	v_readlane_b32 s4, v10, 63
	s_nop 3
	v_mov_b32_e32 v10, s4
	v_fmac_f32_e32 v13, 0xbb800000, v10
	v_fmac_f32_e32 v12, 0xbb800000, v10
	v_mul_f32_e32 v13, v13, v13
	v_fmac_f32_e32 v14, 0xbb800000, v10
	v_fmac_f32_e32 v13, v12, v12
	v_fmac_f32_e32 v11, 0xbb800000, v10
	v_fmac_f32_e32 v13, v14, v14
	v_fmac_f32_e32 v13, v11, v11
	s_nop 1
	v_add_f32_dpp v13, v13, v13 quad_perm:[1,0,3,2] row_mask:0xf bank_mask:0xf
	s_nop 1
	v_add_f32_dpp v13, v13, v13 quad_perm:[2,3,0,1] row_mask:0xf bank_mask:0xf
	s_nop 1
	v_add_f32_dpp v13, v13, v13 row_half_mirror row_mask:0xf bank_mask:0xf
	s_nop 1
	v_add_f32_dpp v13, v13, v13 row_mirror row_mask:0xf bank_mask:0xf
	s_nop 1
	v_add_f32_dpp v13, v13, v13 row_bcast:15 row_mask:0xa bank_mask:0xf
	s_nop 1
	v_add_f32_dpp v13, v13, v13 row_bcast:31 row_mask:0xc bank_mask:0xf
	s_nop 1
	v_readlane_b32 s5, v13, 63
	s_nop 3
	v_mov_b32_e32 v11, s5
	v_fmamk_f32 v11, v11, 0x3b800000, v239
	v_rsq_f32_e32 v11, v11
	v_mul_f32_e32 v10, 0x3b800000, v10
	s_and_saveexec_b64 s[2:3], vcc
	s_nop 0
	ds_write_b64 v9, v[10:11] offset:88
	s_or_b64 exec, exec, s[2:3]
	s_waitcnt vmcnt(3)
	v_lshlrev_b32_e32 v12, 16, v106
	v_and_b32_e32 v13, 0xffff0000, v106
	v_lshlrev_b32_e32 v14, 16, v107
	v_and_b32_e32 v11, 0xffff0000, v107
	v_add_f32_e32 v10, v12, v13
	v_add_f32_e32 v10, v10, v14
	v_add_f32_e32 v10, v10, v11
	s_nop 1
	v_add_f32_dpp v10, v10, v10 quad_perm:[1,0,3,2] row_mask:0xf bank_mask:0xf
	s_nop 1
	v_add_f32_dpp v10, v10, v10 quad_perm:[2,3,0,1] row_mask:0xf bank_mask:0xf
	s_nop 1
	v_add_f32_dpp v10, v10, v10 row_half_mirror row_mask:0xf bank_mask:0xf
	s_nop 1
	v_add_f32_dpp v10, v10, v10 row_mirror row_mask:0xf bank_mask:0xf
	s_nop 1
	v_add_f32_dpp v10, v10, v10 row_bcast:15 row_mask:0xa bank_mask:0xf
	s_nop 1
	v_add_f32_dpp v10, v10, v10 row_bcast:31 row_mask:0xc bank_mask:0xf
	s_nop 1
	v_readlane_b32 s4, v10, 63
	s_nop 3
	v_mov_b32_e32 v10, s4
	v_fmac_f32_e32 v13, 0xbb800000, v10
	v_fmac_f32_e32 v12, 0xbb800000, v10
	v_mul_f32_e32 v13, v13, v13
	v_fmac_f32_e32 v14, 0xbb800000, v10
	v_fmac_f32_e32 v13, v12, v12
	v_fmac_f32_e32 v11, 0xbb800000, v10
	v_fmac_f32_e32 v13, v14, v14
	v_fmac_f32_e32 v13, v11, v11
	s_nop 1
	v_add_f32_dpp v13, v13, v13 quad_perm:[1,0,3,2] row_mask:0xf bank_mask:0xf
	s_nop 1
	v_add_f32_dpp v13, v13, v13 quad_perm:[2,3,0,1] row_mask:0xf bank_mask:0xf
	s_nop 1
	v_add_f32_dpp v13, v13, v13 row_half_mirror row_mask:0xf bank_mask:0xf
	s_nop 1
	v_add_f32_dpp v13, v13, v13 row_mirror row_mask:0xf bank_mask:0xf
	s_nop 1
	v_add_f32_dpp v13, v13, v13 row_bcast:15 row_mask:0xa bank_mask:0xf
	s_nop 1
	v_add_f32_dpp v13, v13, v13 row_bcast:31 row_mask:0xc bank_mask:0xf
	s_nop 1
	v_readlane_b32 s5, v13, 63
	s_nop 3
	v_mov_b32_e32 v11, s5
	v_fmamk_f32 v11, v11, 0x3b800000, v239
	v_rsq_f32_e32 v11, v11
	v_mul_f32_e32 v10, 0x3b800000, v10
	s_and_saveexec_b64 s[2:3], vcc
	s_nop 0
	ds_write_b64 v9, v[10:11] offset:96
	s_or_b64 exec, exec, s[2:3]
	s_waitcnt vmcnt(2)
; __device__ __forceinline__ float frsq(float x) { return __builtin_amdgcn_rsqf(x); }
; __device__ __forceinline__ float wave_sum(float v) {
; #pragma unroll
;     for (int d = 1; d < 64; d <<= 1) v += __shfl_xor(v, d);
;     return v;
; }
; __device__ __forceinline__ void sgu_unit(LAS unsigned char* lds, int b, int n, int g, const bf16_t* V, bf16_t* U, const float* ln_g, const float* ln_b, const float* w_s, const float* b_s, bool dry) {
;     ...
;     for (int rr = 0; rr < 16; ++rr) {
;         const int s = wid * 16 + rr;
;         const u32x2 raw = *(const u32x2*)(V + (size_t)(r0 + s) * 1024 + g * 256 + lane * 4);
;         const float x0 = bflo(raw.x), x1 = bfhi(raw.x), x2 = bflo(raw.y), x3 = bfhi(raw.y);
;         const float mean = wave_sum(x0 + x1 + x2 + x3) * (1.f / 256.f);
;         const float d0 = x0 - mean, d1 = x1 - mean, d2 = x2 - mean, d3 = x3 - mean;
;         const float var = wave_sum(d0 * d0 + d1 * d1 + d2 * d2 + d3 * d3) * (1.f / 256.f);
;         if (lane == 0) { st[2 * s] = mean; st[2 * s + 1] = frsq(var + EPS); }
;     }
	v_lshlrev_b32_e32 v12, 16, v108
	v_and_b32_e32 v13, 0xffff0000, v108
	v_lshlrev_b32_e32 v14, 16, v109
	v_and_b32_e32 v11, 0xffff0000, v109
	v_add_f32_e32 v10, v12, v13
	v_add_f32_e32 v10, v10, v14
	v_add_f32_e32 v10, v10, v11
	s_nop 1
	v_add_f32_dpp v10, v10, v10 quad_perm:[1,0,3,2] row_mask:0xf bank_mask:0xf
	s_nop 1
	v_add_f32_dpp v10, v10, v10 quad_perm:[2,3,0,1] row_mask:0xf bank_mask:0xf
	s_nop 1
	v_add_f32_dpp v10, v10, v10 row_half_mirror row_mask:0xf bank_mask:0xf
	s_nop 1
	v_add_f32_dpp v10, v10, v10 row_mirror row_mask:0xf bank_mask:0xf
	s_nop 1
	v_add_f32_dpp v10, v10, v10 row_bcast:15 row_mask:0xa bank_mask:0xf
	s_nop 1
	v_add_f32_dpp v10, v10, v10 row_bcast:31 row_mask:0xc bank_mask:0xf
	s_nop 1
	v_readlane_b32 s4, v10, 63
	s_nop 3
	v_mov_b32_e32 v10, s4
	v_fmac_f32_e32 v13, 0xbb800000, v10
	v_fmac_f32_e32 v12, 0xbb800000, v10
	v_mul_f32_e32 v13, v13, v13
	v_fmac_f32_e32 v14, 0xbb800000, v10
	v_fmac_f32_e32 v13, v12, v12
	v_fmac_f32_e32 v11, 0xbb800000, v10
	v_fmac_f32_e32 v13, v14, v14
	v_fmac_f32_e32 v13, v11, v11
	s_nop 1
	v_add_f32_dpp v13, v13, v13 quad_perm:[1,0,3,2] row_mask:0xf bank_mask:0xf
	s_nop 1
	v_add_f32_dpp v13, v13, v13 quad_perm:[2,3,0,1] row_mask:0xf bank_mask:0xf
	s_nop 1
	v_add_f32_dpp v13, v13, v13 row_half_mirror row_mask:0xf bank_mask:0xf
	s_nop 1
	v_add_f32_dpp v13, v13, v13 row_mirror row_mask:0xf bank_mask:0xf
	s_nop 1
	v_add_f32_dpp v13, v13, v13 row_bcast:15 row_mask:0xa bank_mask:0xf
	s_nop 1
	v_add_f32_dpp v13, v13, v13 row_bcast:31 row_mask:0xc bank_mask:0xf
	s_nop 1
	v_readlane_b32 s5, v13, 63
	s_nop 3
	v_mov_b32_e32 v11, s5
	v_fmamk_f32 v11, v11, 0x3b800000, v239
	v_rsq_f32_e32 v11, v11
	v_mul_f32_e32 v10, 0x3b800000, v10
	s_and_saveexec_b64 s[2:3], vcc
	s_nop 0
	ds_write_b64 v9, v[10:11] offset:104
	s_or_b64 exec, exec, s[2:3]
	s_waitcnt vmcnt(1)
	v_lshlrev_b32_e32 v12, 16, v110
	v_and_b32_e32 v13, 0xffff0000, v110
	v_lshlrev_b32_e32 v14, 16, v111
	v_and_b32_e32 v11, 0xffff0000, v111
	v_add_f32_e32 v10, v12, v13
	v_add_f32_e32 v10, v10, v14
	v_add_f32_e32 v10, v10, v11
	s_nop 1
	v_add_f32_dpp v10, v10, v10 quad_perm:[1,0,3,2] row_mask:0xf bank_mask:0xf
	s_nop 1
	v_add_f32_dpp v10, v10, v10 quad_perm:[2,3,0,1] row_mask:0xf bank_mask:0xf
	s_nop 1
	v_add_f32_dpp v10, v10, v10 row_half_mirror row_mask:0xf bank_mask:0xf
	s_nop 1
	v_add_f32_dpp v10, v10, v10 row_mirror row_mask:0xf bank_mask:0xf
	s_nop 1
	v_add_f32_dpp v10, v10, v10 row_bcast:15 row_mask:0xa bank_mask:0xf
	s_nop 1
	v_add_f32_dpp v10, v10, v10 row_bcast:31 row_mask:0xc bank_mask:0xf
	s_nop 1
	v_readlane_b32 s4, v10, 63
	s_nop 3
	v_mov_b32_e32 v10, s4
	v_fmac_f32_e32 v13, 0xbb800000, v10
	v_fmac_f32_e32 v12, 0xbb800000, v10
	v_mul_f32_e32 v13, v13, v13
	v_fmac_f32_e32 v14, 0xbb800000, v10
	v_fmac_f32_e32 v13, v12, v12
	v_fmac_f32_e32 v11, 0xbb800000, v10
	v_fmac_f32_e32 v13, v14, v14
	v_fmac_f32_e32 v13, v11, v11
	s_nop 1
	v_add_f32_dpp v13, v13, v13 quad_perm:[1,0,3,2] row_mask:0xf bank_mask:0xf
	s_nop 1
	v_add_f32_dpp v13, v13, v13 quad_perm:[2,3,0,1] row_mask:0xf bank_mask:0xf
	s_nop 1
	v_add_f32_dpp v13, v13, v13 row_half_mirror row_mask:0xf bank_mask:0xf
	s_nop 1
	v_add_f32_dpp v13, v13, v13 row_mirror row_mask:0xf bank_mask:0xf
	s_nop 1
	v_add_f32_dpp v13, v13, v13 row_bcast:15 row_mask:0xa bank_mask:0xf
	s_nop 1
	v_add_f32_dpp v13, v13, v13 row_bcast:31 row_mask:0xc bank_mask:0xf
	s_nop 1
	v_readlane_b32 s5, v13, 63
	s_nop 3
	v_mov_b32_e32 v11, s5
	v_fmamk_f32 v11, v11, 0x3b800000, v239
	v_rsq_f32_e32 v11, v11
	v_mul_f32_e32 v10, 0x3b800000, v10
	s_and_saveexec_b64 s[2:3], vcc
	s_nop 0
	ds_write_b64 v9, v[10:11] offset:112
	s_or_b64 exec, exec, s[2:3]
	s_waitcnt vmcnt(0)
	v_lshlrev_b32_e32 v12, 16, v112
	v_and_b32_e32 v13, 0xffff0000, v112
	v_lshlrev_b32_e32 v14, 16, v113
	v_and_b32_e32 v11, 0xffff0000, v113
	v_add_f32_e32 v10, v12, v13
	v_add_f32_e32 v10, v10, v14
	v_add_f32_e32 v10, v10, v11
	s_nop 1
	v_add_f32_dpp v10, v10, v10 quad_perm:[1,0,3,2] row_mask:0xf bank_mask:0xf
	s_nop 1
	v_add_f32_dpp v10, v10, v10 quad_perm:[2,3,0,1] row_mask:0xf bank_mask:0xf
	s_nop 1
	v_add_f32_dpp v10, v10, v10 row_half_mirror row_mask:0xf bank_mask:0xf
	s_nop 1
	v_add_f32_dpp v10, v10, v10 row_mirror row_mask:0xf bank_mask:0xf
	s_nop 1
	v_add_f32_dpp v10, v10, v10 row_bcast:15 row_mask:0xa bank_mask:0xf
	s_nop 1
	v_add_f32_dpp v10, v10, v10 row_bcast:31 row_mask:0xc bank_mask:0xf
	s_nop 1
	v_readlane_b32 s4, v10, 63
	s_nop 3
	v_mov_b32_e32 v10, s4
	v_fmac_f32_e32 v13, 0xbb800000, v10
	v_fmac_f32_e32 v12, 0xbb800000, v10
	v_mul_f32_e32 v13, v13, v13
	v_fmac_f32_e32 v14, 0xbb800000, v10
	v_fmac_f32_e32 v13, v12, v12
	v_fmac_f32_e32 v11, 0xbb800000, v10
	v_fmac_f32_e32 v13, v14, v14
	v_fmac_f32_e32 v13, v11, v11
	s_nop 1
	v_add_f32_dpp v13, v13, v13 quad_perm:[1,0,3,2] row_mask:0xf bank_mask:0xf
	s_nop 1
	v_add_f32_dpp v13, v13, v13 quad_perm:[2,3,0,1] row_mask:0xf bank_mask:0xf
	s_nop 1
	v_add_f32_dpp v13, v13, v13 row_half_mirror row_mask:0xf bank_mask:0xf
	s_nop 1
	v_add_f32_dpp v13, v13, v13 row_mirror row_mask:0xf bank_mask:0xf
	s_nop 1
	v_add_f32_dpp v13, v13, v13 row_bcast:15 row_mask:0xa bank_mask:0xf
	s_nop 1
	v_add_f32_dpp v13, v13, v13 row_bcast:31 row_mask:0xc bank_mask:0xf
	s_nop 1
	v_readlane_b32 s5, v13, 63
	s_nop 3
	v_mov_b32_e32 v11, s5
	v_fmamk_f32 v11, v11, 0x3b800000, v239
	v_rsq_f32_e32 v11, v11
	v_mul_f32_e32 v10, 0x3b800000, v10
	s_and_saveexec_b64 s[2:3], vcc
	s_nop 0
	ds_write_b64 v9, v[10:11] offset:120
	s_or_b64 exec, exec, s[2:3]

; __device__ __forceinline__ unsigned cvt_pk_bf16(float lo, float hi) { const f32x2_t v = {lo, hi}; const bf16x2_t b = __builtin_convertvector(v, bf16x2_t); return __builtin_bit_cast(unsigned, b); }
; __device__ __forceinline__ void sgu_unit(LAS unsigned char* lds, int b, int n, int g, const bf16_t* V, bf16_t* U, const float* ln_g, const float* ln_b, const float* w_s, const float* b_s, bool dry) {
;     ...
;     const float bs = b_s[g * 128 + t];
;     bf16_t* up = U + (size_t)(r0 + t) * 1024 + g * 256 + fq * 4;
; #pragma unroll
;     for (int nt = 0; nt < 16; ++nt) {
;         const u32x2 uu = *(const u32x2*)(up + nt * 16);
;         u32x2 w; w.x = cvt_pk_bf16(bflo(uu.x) * (acc[nt][0] + bs), bfhi(uu.x) * (acc[nt][1] + bs)); w.y = cvt_pk_bf16(bflo(uu.y) * (acc[nt][2] + bs), bfhi(uu.y) * (acc[nt][3] + bs));
;         if (!dry) *(u32x2*)(up + nt * 16) = w;
;     }
.LBB0_319:
	s_or_b64 exec, exec, s[6:7]
	v_add_u32_e32 v66, s41, v68
	s_lshl_b64 s[4:5], s[96:97], 2
	v_ashrrev_i32_e32 v67, 31, v66
	s_add_u32 s4, s18, s4
	v_lshlrev_b64 v[66:67], 11, v[66:67]
	s_addc_u32 s5, s19, s5
	v_add_u32_e32 v64, v64, v68
	v_lshl_add_u64 v[66:67], s[64:65], 0, v[66:67]
	s_lshl_b32 s28, s2, 1
	v_ashrrev_i32_e32 v65, 31, v64
	v_lshl_add_u64 v[66:67], v[66:67], 0, s[28:29]
	v_lshl_add_u64 v[64:65], v[64:65], 2, s[4:5]
	v_lshl_add_u64 v[66:67], v[66:67], 0, v[160:161]
	global_load_dword v64, v[64:65], off
	s_mov_b64 s[2:3], 0
	global_load_dwordx2 v[68:69], v[66:67], off
	global_load_dwordx2 v[114:115], v[66:67], off offset:32
	global_load_dwordx2 v[116:117], v[66:67], off offset:64
	global_load_dwordx2 v[118:119], v[66:67], off offset:96
	global_load_dwordx2 v[120:121], v[66:67], off offset:128
	global_load_dwordx2 v[122:123], v[66:67], off offset:160
	global_load_dwordx2 v[124:125], v[66:67], off offset:192
	global_load_dwordx2 v[126:127], v[66:67], off offset:224
	global_load_dwordx2 v[128:129], v[66:67], off offset:256
	global_load_dwordx2 v[130:131], v[66:67], off offset:288
	global_load_dwordx2 v[132:133], v[66:67], off offset:320
	global_load_dwordx2 v[134:135], v[66:67], off offset:352
	global_load_dwordx2 v[136:137], v[66:67], off offset:384
	global_load_dwordx2 v[138:139], v[66:67], off offset:416
	global_load_dwordx2 v[140:141], v[66:67], off offset:448
	global_load_dwordx2 v[142:143], v[66:67], off offset:480
	s_waitcnt vmcnt(1)
	v_pk_add_f32 v[60:61], v[64:65], v[60:61] op_sel_hi:[0,1]
	v_pk_add_f32 v[62:63], v[64:65], v[62:63] op_sel_hi:[0,1]
	s_waitcnt vmcnt(0)
	v_lshlrev_b32_e32 v70, 16, v68
	v_and_b32_e32 v71, 0xffff0000, v68
	v_lshlrev_b32_e32 v68, 16, v69
	v_and_b32_e32 v69, 0xffff0000, v69
	v_pk_mul_f32 v[60:61], v[60:61], v[70:71]
	v_pk_mul_f32 v[62:63], v[62:63], v[68:69]
	v_cvt_pk_bf16_f32 v60, v60, v61
	v_cvt_pk_bf16_f32 v61, v62, v63
	global_store_dwordx2 v[66:67], v[60:61], off
	s_nop 1
	v_mov_b64_e32 v[60:61], v[114:115]
	v_pk_add_f32 v[56:57], v[56:57], v[64:65] op_sel_hi:[1,0]
	v_pk_add_f32 v[58:59], v[58:59], v[64:65] op_sel_hi:[1,0]
	v_pk_add_f32 v[52:53], v[52:53], v[64:65] op_sel_hi:[1,0]
	v_pk_add_f32 v[54:55], v[54:55], v[64:65] op_sel_hi:[1,0]
	v_pk_add_f32 v[48:49], v[48:49], v[64:65] op_sel_hi:[1,0]
	v_pk_add_f32 v[50:51], v[50:51], v[64:65] op_sel_hi:[1,0]
	v_pk_add_f32 v[44:45], v[44:45], v[64:65] op_sel_hi:[1,0]
	v_pk_add_f32 v[46:47], v[46:47], v[64:65] op_sel_hi:[1,0]
	v_pk_add_f32 v[40:41], v[40:41], v[64:65] op_sel_hi:[1,0]
	v_pk_add_f32 v[42:43], v[42:43], v[64:65] op_sel_hi:[1,0]
	v_pk_add_f32 v[36:37], v[36:37], v[64:65] op_sel_hi:[1,0]
	v_pk_add_f32 v[38:39], v[38:39], v[64:65] op_sel_hi:[1,0]
	v_pk_add_f32 v[32:33], v[32:33], v[64:65] op_sel_hi:[1,0]
	v_pk_add_f32 v[34:35], v[34:35], v[64:65] op_sel_hi:[1,0]
	v_pk_add_f32 v[28:29], v[28:29], v[64:65] op_sel_hi:[1,0]
	v_pk_add_f32 v[30:31], v[30:31], v[64:65] op_sel_hi:[1,0]
	v_pk_add_f32 v[24:25], v[24:25], v[64:65] op_sel_hi:[1,0]
	v_pk_add_f32 v[26:27], v[26:27], v[64:65] op_sel_hi:[1,0]
	v_pk_add_f32 v[20:21], v[20:21], v[64:65] op_sel_hi:[1,0]
	v_pk_add_f32 v[22:23], v[22:23], v[64:65] op_sel_hi:[1,0]
	v_pk_add_f32 v[16:17], v[16:17], v[64:65] op_sel_hi:[1,0]
	v_pk_add_f32 v[18:19], v[18:19], v[64:65] op_sel_hi:[1,0]
	v_pk_add_f32 v[12:13], v[12:13], v[64:65] op_sel_hi:[1,0]
	v_pk_add_f32 v[14:15], v[14:15], v[64:65] op_sel_hi:[1,0]
	v_pk_add_f32 v[8:9], v[8:9], v[64:65] op_sel_hi:[1,0]
	v_pk_add_f32 v[10:11], v[10:11], v[64:65] op_sel_hi:[1,0]
	v_pk_add_f32 v[4:5], v[4:5], v[64:65] op_sel_hi:[1,0]
	v_pk_add_f32 v[6:7], v[6:7], v[64:65] op_sel_hi:[1,0]
	v_pk_add_f32 v[0:1], v[0:1], v[64:65] op_sel_hi:[1,0]
	v_pk_add_f32 v[2:3], v[2:3], v[64:65] op_sel_hi:[1,0]
	v_lshlrev_b32_e32 v62, 16, v60
	v_and_b32_e32 v63, 0xffff0000, v60
	v_lshlrev_b32_e32 v60, 16, v61
	v_and_b32_e32 v61, 0xffff0000, v61
	v_pk_mul_f32 v[56:57], v[56:57], v[62:63]
	v_pk_mul_f32 v[58:59], v[58:59], v[60:61]
	v_cvt_pk_bf16_f32 v56, v56, v57
	v_cvt_pk_bf16_f32 v57, v58, v59
	global_store_dwordx2 v[66:67], v[56:57], off offset:32
	s_nop 1
	v_mov_b64_e32 v[56:57], v[116:117]
	v_lshlrev_b32_e32 v58, 16, v56
	v_and_b32_e32 v59, 0xffff0000, v56
	v_lshlrev_b32_e32 v56, 16, v57
	v_and_b32_e32 v57, 0xffff0000, v57
	v_pk_mul_f32 v[52:53], v[52:53], v[58:59]
	v_pk_mul_f32 v[54:55], v[54:55], v[56:57]
	v_cvt_pk_bf16_f32 v52, v52, v53
	v_cvt_pk_bf16_f32 v53, v54, v55
	global_store_dwordx2 v[66:67], v[52:53], off offset:64
	s_nop 1
	v_mov_b64_e32 v[52:53], v[118:119]
	v_lshlrev_b32_e32 v54, 16, v52
	v_and_b32_e32 v55, 0xffff0000, v52
	v_lshlrev_b32_e32 v52, 16, v53
	v_and_b32_e32 v53, 0xffff0000, v53
	v_pk_mul_f32 v[48:49], v[48:49], v[54:55]
	v_pk_mul_f32 v[50:51], v[50:51], v[52:53]
; __device__ __forceinline__ unsigned cvt_pk_bf16(float lo, float hi) { const f32x2_t v = {lo, hi}; const bf16x2_t b = __builtin_convertvector(v, bf16x2_t); return __builtin_bit_cast(unsigned, b); }
; __device__ __forceinline__ void sgu_unit(LAS unsigned char* lds, int b, int n, int g, const bf16_t* V, bf16_t* U, const float* ln_g, const float* ln_b, const float* w_s, const float* b_s, bool dry) {
;     ...
;     for (int nt = 0; nt < 16; ++nt) {
;         const u32x2 uu = *(const u32x2*)(up + nt * 16);
;         u32x2 w; w.x = cvt_pk_bf16(bflo(uu.x) * (acc[nt][0] + bs), bfhi(uu.x) * (acc[nt][1] + bs)); w.y = cvt_pk_bf16(bflo(uu.y) * (acc[nt][2] + bs), bfhi(uu.y) * (acc[nt][3] + bs));
;         if (!dry) *(u32x2*)(up + nt * 16) = w;
;     }
	v_cvt_pk_bf16_f32 v48, v48, v49
	v_cvt_pk_bf16_f32 v49, v50, v51
	global_store_dwordx2 v[66:67], v[48:49], off offset:96
	s_nop 1
	v_mov_b64_e32 v[48:49], v[120:121]
	v_lshlrev_b32_e32 v50, 16, v48
	v_and_b32_e32 v51, 0xffff0000, v48
	v_lshlrev_b32_e32 v48, 16, v49
	v_and_b32_e32 v49, 0xffff0000, v49
	v_pk_mul_f32 v[44:45], v[44:45], v[50:51]
	v_pk_mul_f32 v[46:47], v[46:47], v[48:49]
	v_cvt_pk_bf16_f32 v44, v44, v45
	v_cvt_pk_bf16_f32 v45, v46, v47
	global_store_dwordx2 v[66:67], v[44:45], off offset:128
	s_nop 1
	v_mov_b64_e32 v[44:45], v[122:123]
	v_lshlrev_b32_e32 v46, 16, v44
	v_and_b32_e32 v47, 0xffff0000, v44
	v_lshlrev_b32_e32 v44, 16, v45
	v_and_b32_e32 v45, 0xffff0000, v45
	v_pk_mul_f32 v[40:41], v[40:41], v[46:47]
	v_pk_mul_f32 v[42:43], v[42:43], v[44:45]
	v_cvt_pk_bf16_f32 v40, v40, v41
	v_cvt_pk_bf16_f32 v41, v42, v43
	global_store_dwordx2 v[66:67], v[40:41], off offset:160
	s_nop 1
	v_mov_b64_e32 v[40:41], v[124:125]
	v_lshlrev_b32_e32 v42, 16, v40
	v_and_b32_e32 v43, 0xffff0000, v40
	v_lshlrev_b32_e32 v40, 16, v41
	v_and_b32_e32 v41, 0xffff0000, v41
	v_pk_mul_f32 v[36:37], v[36:37], v[42:43]
	v_pk_mul_f32 v[38:39], v[38:39], v[40:41]
	v_cvt_pk_bf16_f32 v36, v36, v37
	v_cvt_pk_bf16_f32 v37, v38, v39
	global_store_dwordx2 v[66:67], v[36:37], off offset:192
	s_nop 1
	v_mov_b64_e32 v[36:37], v[126:127]
	v_lshlrev_b32_e32 v38, 16, v36
	v_and_b32_e32 v39, 0xffff0000, v36
	v_lshlrev_b32_e32 v36, 16, v37
	v_and_b32_e32 v37, 0xffff0000, v37
	v_pk_mul_f32 v[32:33], v[32:33], v[38:39]
	v_pk_mul_f32 v[34:35], v[34:35], v[36:37]
	v_cvt_pk_bf16_f32 v32, v32, v33
	v_cvt_pk_bf16_f32 v33, v34, v35
	global_store_dwordx2 v[66:67], v[32:33], off offset:224
	s_nop 1
	v_mov_b64_e32 v[32:33], v[128:129]
	v_lshlrev_b32_e32 v34, 16, v32
	v_and_b32_e32 v35, 0xffff0000, v32
	v_lshlrev_b32_e32 v32, 16, v33
	v_and_b32_e32 v33, 0xffff0000, v33
	v_pk_mul_f32 v[28:29], v[28:29], v[34:35]
	v_pk_mul_f32 v[30:31], v[30:31], v[32:33]
	v_cvt_pk_bf16_f32 v28, v28, v29
	v_cvt_pk_bf16_f32 v29, v30, v31
	global_store_dwordx2 v[66:67], v[28:29], off offset:256
	s_nop 1
	v_mov_b64_e32 v[28:29], v[130:131]
	v_lshlrev_b32_e32 v30, 16, v28
	v_and_b32_e32 v31, 0xffff0000, v28
	v_lshlrev_b32_e32 v28, 16, v29
	v_and_b32_e32 v29, 0xffff0000, v29
	v_pk_mul_f32 v[24:25], v[24:25], v[30:31]
	v_pk_mul_f32 v[26:27], v[26:27], v[28:29]
	v_cvt_pk_bf16_f32 v24, v24, v25
	v_cvt_pk_bf16_f32 v25, v26, v27
	global_store_dwordx2 v[66:67], v[24:25], off offset:288
	s_nop 1
	v_mov_b64_e32 v[24:25], v[132:133]
	v_lshlrev_b32_e32 v26, 16, v24
	v_and_b32_e32 v27, 0xffff0000, v24
	v_lshlrev_b32_e32 v24, 16, v25
	v_and_b32_e32 v25, 0xffff0000, v25
	v_pk_mul_f32 v[20:21], v[20:21], v[26:27]
	v_pk_mul_f32 v[22:23], v[22:23], v[24:25]
	v_cvt_pk_bf16_f32 v20, v20, v21
	v_cvt_pk_bf16_f32 v21, v22, v23
	global_store_dwordx2 v[66:67], v[20:21], off offset:320
	s_nop 1
	v_mov_b64_e32 v[20:21], v[134:135]
	v_lshlrev_b32_e32 v22, 16, v20
	v_and_b32_e32 v23, 0xffff0000, v20
	v_lshlrev_b32_e32 v20, 16, v21
	v_and_b32_e32 v21, 0xffff0000, v21
	v_pk_mul_f32 v[16:17], v[16:17], v[22:23]
	v_pk_mul_f32 v[18:19], v[18:19], v[20:21]
	v_cvt_pk_bf16_f32 v16, v16, v17
	v_cvt_pk_bf16_f32 v17, v18, v19
	global_store_dwordx2 v[66:67], v[16:17], off offset:352
	s_nop 1
	v_mov_b64_e32 v[16:17], v[136:137]
	v_lshlrev_b32_e32 v18, 16, v16
	v_and_b32_e32 v19, 0xffff0000, v16
	v_lshlrev_b32_e32 v16, 16, v17
	v_and_b32_e32 v17, 0xffff0000, v17
	v_pk_mul_f32 v[12:13], v[12:13], v[18:19]
	v_pk_mul_f32 v[14:15], v[14:15], v[16:17]
	v_cvt_pk_bf16_f32 v12, v12, v13
	v_cvt_pk_bf16_f32 v13, v14, v15
	global_store_dwordx2 v[66:67], v[12:13], off offset:384
	s_nop 1
	v_mov_b64_e32 v[12:13], v[138:139]
	v_lshlrev_b32_e32 v14, 16, v12
	v_and_b32_e32 v15, 0xffff0000, v12
	v_lshlrev_b32_e32 v12, 16, v13
	v_and_b32_e32 v13, 0xffff0000, v13
	v_pk_mul_f32 v[8:9], v[8:9], v[14:15]
	v_pk_mul_f32 v[10:11], v[10:11], v[12:13]
	v_cvt_pk_bf16_f32 v8, v8, v9
	v_cvt_pk_bf16_f32 v9, v10, v11
	global_store_dwordx2 v[66:67], v[8:9], off offset:416
	s_nop 1
	v_mov_b64_e32 v[8:9], v[140:141]
	v_lshlrev_b32_e32 v10, 16, v8
	v_and_b32_e32 v11, 0xffff0000, v8
	v_lshlrev_b32_e32 v8, 16, v9
	v_and_b32_e32 v9, 0xffff0000, v9
	v_pk_mul_f32 v[4:5], v[4:5], v[10:11]
	v_pk_mul_f32 v[6:7], v[6:7], v[8:9]
	v_cvt_pk_bf16_f32 v4, v4, v5
	v_cvt_pk_bf16_f32 v5, v6, v7
	global_store_dwordx2 v[66:67], v[4:5], off offset:448
	s_nop 1
	v_mov_b64_e32 v[4:5], v[142:143]
	v_lshlrev_b32_e32 v6, 16, v4
	v_and_b32_e32 v7, 0xffff0000, v4
	v_lshlrev_b32_e32 v4, 16, v5
	v_and_b32_e32 v5, 0xffff0000, v5
	v_pk_mul_f32 v[0:1], v[0:1], v[6:7]
	v_pk_mul_f32 v[2:3], v[2:3], v[4:5]
	v_cvt_pk_bf16_f32 v0, v0, v1
	v_cvt_pk_bf16_f32 v1, v2, v3
	global_store_dwordx2 v[66:67], v[0:1], off offset:480

; #define LAS __attribute__((address_space(3)))
; __device__ __forceinline__ void gla_pre_unit(LAS unsigned char* lds, int b, int h, int ci, unsigned char* ws, const float* w_gate, const float* b_gate) {
;     ...
;     if (tid < 256) *(LAS f32x4*)(GAL + tid * 4) = *(const f32x4*)(GA + (size_t)rc * 16 + tid * 4);
; #pragma unroll
;     for (int i = 0; i < 4; ++i) {
;         const int vc = (wid + 8 * i) * 8;
;         const u32x4 raw = *(const u32x4*)(GV + (size_t)(rc + lane) * 1024 + h * 256 + vc);
;         LAS bf16_t* vp = VT + vc * 72 + lane;
;         vp[0 * 72] = (bf16_t)(raw.x & 0xffffu); vp[1 * 72] = (bf16_t)(raw.x >> 16); vp[2 * 72] = (bf16_t)(raw.y & 0xffffu); vp[3 * 72] = (bf16_t)(raw.y >> 16);
;         vp[4 * 72] = (bf16_t)(raw.z & 0xffffu); vp[5 * 72] = (bf16_t)(raw.z >> 16); vp[6 * 72] = (bf16_t)(raw.w & 0xffffu); vp[7 * 72] = (bf16_t)(raw.w >> 16);
;     }
;     float wg[16];
; #pragma unroll
;     for (int j = 0; j < 16; ++j) wg[j] = w_gate[j * 512 + h * 128 + c];
;     const float bg = b_gate[h * 128 + c];
;     unsigned short qraw[16], kraw[16];
; #pragma unroll
;     for (int tt = 0; tt < 16; ++tt) { const int t = seg * 16 + tt; qraw[tt] = GQ[(size_t)(rc + t) * 512 + h * 128 + c]; kraw[tt] = GK[(size_t)(rc + t) * 512 + h * 128 + c]; }
.LBB0_323:
	s_or_b64 exec, exec, s[2:3]
	s_load_dwordx4 s[16:19], s[76:77], 0x60
	s_bfe_u32 s15, s62, 0x20005
	v_and_b32_e32 v17, 63, v6
	v_or_b32_e32 v4, s4, v17
	v_ashrrev_i32_e32 v5, 31, v4
	s_waitcnt lgkmcnt(0)
	s_add_u32 s12, s16, s72
	s_addc_u32 s13, s17, s73
	s_lshl_b64 s[2:3], s[96:97], 2
	s_add_u32 s6, s18, s2
	v_ashrrev_i32_e32 v16, 6, v6
	v_lshlrev_b64 v[4:5], 11, v[4:5]
	s_addc_u32 s7, s19, s3
	v_lshlrev_b32_e32 v2, 3, v16
	v_lshl_add_u64 v[4:5], s[10:11], 0, v[4:5]
	s_lshl_b32 s28, s15, 9
	v_lshl_add_u64 v[4:5], v[4:5], 0, s[28:29]
	v_ashrrev_i32_e32 v3, 31, v2
	s_movk_i32 s2, 0x480
	v_lshlrev_b32_e32 v1, 1, v17
	v_lshl_add_u64 v[8:9], v[2:3], 1, v[4:5]
	v_mul_lo_u32 v2, v16, s2
	v_readlane_b32 s2, v255, 5
	v_and_b32_e32 v0, 0x7f, v6
	v_lshl_or_b32 v12, s15, 7, v0
	v_add3_u32 v1, s2, v1, v2
	global_load_dwordx4 v[2:5], v[8:9], off
	global_load_dwordx4 v[144:147], v[8:9], off offset:128
	global_load_dwordx4 v[148:151], v[8:9], off offset:256
	global_load_dwordx4 v[152:155], v[8:9], off offset:384
	v_lshlrev_b32_e32 v160, 2, v12
	s_movk_i32 s2, 0x1000
	v_ashrrev_i32_e32 v7, 7, v6
	s_waitcnt vmcnt(18)
	v_lshlrev_b32_e32 v57, 1, v12
	s_mov_b32 s3, 0xbfb8aa3b
	s_waitcnt vmcnt(0)
	ds_write_b16 v1, v2
	ds_write_b16_d16_hi v1, v2 offset:144
	ds_write_b16 v1, v3 offset:288
	ds_write_b16_d16_hi v1, v3 offset:432
	ds_write_b16 v1, v4 offset:576
	ds_write_b16_d16_hi v1, v4 offset:720
	ds_write_b16 v1, v5 offset:864
	ds_write_b16_d16_hi v1, v5 offset:1008
	ds_write_b16 v1, v144 offset:9216
	ds_write_b16_d16_hi v1, v144 offset:9360
	ds_write_b16 v1, v145 offset:9504
	ds_write_b16_d16_hi v1, v145 offset:9648
	ds_write_b16 v1, v146 offset:9792
	ds_write_b16_d16_hi v1, v146 offset:9936
	ds_write_b16 v1, v147 offset:10080
	ds_write_b16_d16_hi v1, v147 offset:10224
	ds_write_b16 v1, v148 offset:18432
	ds_write_b16_d16_hi v1, v148 offset:18576
	ds_write_b16 v1, v149 offset:18720
	ds_write_b16_d16_hi v1, v149 offset:18864
	ds_write_b16 v1, v150 offset:19008
	ds_write_b16_d16_hi v1, v150 offset:19152
	ds_write_b16 v1, v151 offset:19296
	ds_write_b16_d16_hi v1, v151 offset:19440
	ds_write_b16 v1, v152 offset:27648
	ds_write_b16_d16_hi v1, v152 offset:27792
	ds_write_b16 v1, v153 offset:27936
	ds_write_b16_d16_hi v1, v153 offset:28080
	ds_write_b16 v1, v154 offset:28224
	ds_write_b16_d16_hi v1, v154 offset:28368
	ds_write_b16 v1, v155 offset:28512
	ds_write_b16_d16_hi v1, v155 offset:28656
	v_lshl_add_u64 v[2:3], s[12:13], 0, v[160:161]
	v_add_co_u32_e32 v8, vcc, s2, v2
	s_movk_i32 s2, 0x2000
	s_nop 0
	v_addc_co_u32_e32 v9, vcc, 0, v3, vcc
	v_add_co_u32_e32 v10, vcc, s2, v2
	global_load_dword v4, v160, s[12:13]
	global_load_dword v40, v160, s[12:13] offset:2048
	v_addc_co_u32_e32 v11, vcc, 0, v3, vcc
	global_load_dword v47, v[10:11], off offset:-4096
	global_load_dword v48, v[8:9], off offset:2048
	global_load_dword v42, v[10:11], off
	global_load_dword v43, v[10:11], off offset:2048
	v_add_co_u32_e32 v8, vcc, s26, v2
	s_movk_i32 s2, 0x4000
	s_nop 0
	v_addc_co_u32_e32 v9, vcc, 0, v3, vcc
	v_add_co_u32_e32 v10, vcc, s2, v2
	s_movk_i32 s2, 0x5000
	s_nop 0
	v_addc_co_u32_e32 v11, vcc, 0, v3, vcc
	global_load_dword v44, v[10:11], off offset:-4096
	global_load_dword v45, v[8:9], off offset:2048
	global_load_dword v5, v[10:11], off
	global_load_dword v41, v[10:11], off offset:2048
	v_add_co_u32_e32 v8, vcc, s2, v2
	s_movk_i32 s2, 0x6000
	s_nop 0
	v_addc_co_u32_e32 v9, vcc, 0, v3, vcc
	v_add_co_u32_e32 v10, vcc, s2, v2
	s_movk_i32 s2, 0x7000
	s_nop 0
	v_addc_co_u32_e32 v11, vcc, 0, v3, vcc
	v_add_co_u32_e32 v2, vcc, s2, v2
	v_lshlrev_b32_e32 v1, 4, v7
	s_nop 0
	v_addc_co_u32_e32 v3, vcc, 0, v3, vcc
	global_load_dword v54, v[10:11], off offset:-4096
	global_load_dword v55, v[8:9], off offset:2048
	global_load_dword v50, v[10:11], off
	global_load_dword v51, v[10:11], off offset:2048
	global_load_dword v53, v[2:3], off
	global_load_dword v52, v[2:3], off offset:2048
	global_load_dword v56, v160, s[6:7]
	v_add_u32_e32 v2, s4, v1
	v_ashrrev_i32_e32 v3, 31, v2
	v_lshlrev_b64 v[8:9], 10, v[2:3]
	v_or_b32_e32 v8, v8, v57
	v_lshl_add_u64 v[10:11], s[60:61], 0, v[8:9]
	v_lshl_add_u64 v[8:9], s[66:67], 0, v[8:9]
	global_load_ushort v46, v[10:11], off
	global_load_ushort v49, v[8:9], off
	v_or_b32_e32 v8, 1, v2
	v_ashrrev_i32_e32 v9, 31, v8
	v_lshlrev_b64 v[8:9], 10, v[8:9]
	v_or_b32_e32 v8, v8, v57
	v_lshl_add_u64 v[10:11], s[60:61], 0, v[8:9]
	v_lshl_add_u64 v[8:9], s[66:67], 0, v[8:9]
	global_load_ushort v38, v[10:11], off
	global_load_ushort v39, v[8:9], off
	v_or_b32_e32 v8, 2, v2
	v_ashrrev_i32_e32 v9, 31, v8
	v_lshlrev_b64 v[8:9], 10, v[8:9]
	v_or_b32_e32 v8, v8, v57
	v_lshl_add_u64 v[10:11], s[60:61], 0, v[8:9]
	v_lshl_add_u64 v[8:9], s[66:67], 0, v[8:9]
	global_load_ushort v36, v[10:11], off
	global_load_ushort v37, v[8:9], off
	v_or_b32_e32 v8, 3, v2
	v_ashrrev_i32_e32 v9, 31, v8
	v_lshlrev_b64 v[8:9], 10, v[8:9]
	v_or_b32_e32 v8, v8, v57
	v_lshl_add_u64 v[10:11], s[60:61], 0, v[8:9]
	v_lshl_add_u64 v[8:9], s[66:67], 0, v[8:9]
	global_load_ushort v34, v[10:11], off
	global_load_ushort v35, v[8:9], off
	v_or_b32_e32 v8, 4, v2
	v_ashrrev_i32_e32 v9, 31, v8
	v_lshlrev_b64 v[8:9], 10, v[8:9]
	v_or_b32_e32 v8, v8, v57
	v_lshl_add_u64 v[10:11], s[60:61], 0, v[8:9]
	v_lshl_add_u64 v[8:9], s[66:67], 0, v[8:9]
	global_load_ushort v32, v[10:11], off
	global_load_ushort v33, v[8:9], off
	v_or_b32_e32 v8, 5, v2
	v_ashrrev_i32_e32 v9, 31, v8
	v_lshlrev_b64 v[8:9], 10, v[8:9]
	v_or_b32_e32 v8, v8, v57
	v_lshl_add_u64 v[10:11], s[60:61], 0, v[8:9]
	v_lshl_add_u64 v[8:9], s[66:67], 0, v[8:9]
	global_load_ushort v30, v[10:11], off
	global_load_ushort v31, v[8:9], off
; #define LAS __attribute__((address_space(3)))
; __device__ __forceinline__ float logsigmoidf_(float x) { return fminf(x, 0.f) - LN2 * flog2(1.f + fexp2(-fabsf(x) * LOG2E)); }
; __device__ __forceinline__ void gla_pre_unit(LAS unsigned char* lds, int b, int h, int ci, unsigned char* ws, const float* w_gate, const float* b_gate) {
;     ...
;     for (int tt = 0; tt < 16; ++tt) { const int t = seg * 16 + tt; qraw[tt] = GQ[(size_t)(rc + t) * 512 + h * 128 + c]; kraw[tt] = GK[(size_t)(rc + t) * 512 + h * 128 + c]; }
;     __syncthreads();
;     float bc[16]; float run = 0.f;
; #pragma unroll
;     for (int tt = 0; tt < 16; ++tt) {
;         const int t = seg * 16 + tt; float x = bg;
; #pragma unroll
;         for (int j4 = 0; j4 < 4; ++j4) { const f32x4 a = *(const LAS f32x4*)(GAL + t * 16 + j4 * 4); x += a[0] * wg[j4 * 4] + a[1] * wg[j4 * 4 + 1] + a[2] * wg[j4 * 4 + 2] + a[3] * wg[j4 * 4 + 3]; }
;         run += logsigmoidf_(x) * (1.f / 16.f); bc[tt] = run;
	v_or_b32_e32 v8, 6, v2
	v_ashrrev_i32_e32 v9, 31, v8
	v_lshlrev_b64 v[8:9], 10, v[8:9]
	v_or_b32_e32 v8, v8, v57
	v_lshl_add_u64 v[10:11], s[60:61], 0, v[8:9]
	v_lshl_add_u64 v[8:9], s[66:67], 0, v[8:9]
	global_load_ushort v28, v[10:11], off
	global_load_ushort v29, v[8:9], off
	v_or_b32_e32 v8, 7, v2
	v_ashrrev_i32_e32 v9, 31, v8
	v_lshlrev_b64 v[8:9], 10, v[8:9]
	v_or_b32_e32 v8, v8, v57
	v_lshl_add_u64 v[10:11], s[60:61], 0, v[8:9]
	v_lshl_add_u64 v[8:9], s[66:67], 0, v[8:9]
	global_load_ushort v26, v[10:11], off
	global_load_ushort v27, v[8:9], off
	v_or_b32_e32 v8, 8, v2
	v_ashrrev_i32_e32 v9, 31, v8
	v_lshlrev_b64 v[8:9], 10, v[8:9]
	v_or_b32_e32 v8, v8, v57
	v_lshl_add_u64 v[10:11], s[60:61], 0, v[8:9]
	v_lshl_add_u64 v[8:9], s[66:67], 0, v[8:9]
	global_load_ushort v24, v[10:11], off
	global_load_ushort v25, v[8:9], off
	v_or_b32_e32 v8, 9, v2
	v_ashrrev_i32_e32 v9, 31, v8
	v_lshlrev_b64 v[8:9], 10, v[8:9]
	v_or_b32_e32 v8, v8, v57
	v_lshl_add_u64 v[10:11], s[60:61], 0, v[8:9]
	v_lshl_add_u64 v[8:9], s[66:67], 0, v[8:9]
	global_load_ushort v22, v[10:11], off
	global_load_ushort v23, v[8:9], off
	v_or_b32_e32 v8, 10, v2
	v_ashrrev_i32_e32 v9, 31, v8
	v_lshlrev_b64 v[8:9], 10, v[8:9]
	v_or_b32_e32 v8, v8, v57
	v_lshl_add_u64 v[10:11], s[60:61], 0, v[8:9]
	v_lshl_add_u64 v[8:9], s[66:67], 0, v[8:9]
	global_load_ushort v20, v[10:11], off
	global_load_ushort v21, v[8:9], off
	v_or_b32_e32 v8, 11, v2
	v_ashrrev_i32_e32 v9, 31, v8
	v_lshlrev_b64 v[8:9], 10, v[8:9]
	v_or_b32_e32 v8, v8, v57
	v_lshl_add_u64 v[10:11], s[60:61], 0, v[8:9]
	v_lshl_add_u64 v[8:9], s[66:67], 0, v[8:9]
	global_load_ushort v18, v[10:11], off
	global_load_ushort v19, v[8:9], off
	v_or_b32_e32 v8, 12, v2
	v_ashrrev_i32_e32 v9, 31, v8
	v_lshlrev_b64 v[8:9], 10, v[8:9]
	v_or_b32_e32 v8, v8, v57
	v_lshl_add_u64 v[10:11], s[60:61], 0, v[8:9]
	v_lshl_add_u64 v[8:9], s[66:67], 0, v[8:9]
	global_load_ushort v14, v[10:11], off
	global_load_ushort v15, v[8:9], off
	v_or_b32_e32 v8, 13, v2
	v_ashrrev_i32_e32 v9, 31, v8
	v_lshlrev_b64 v[8:9], 10, v[8:9]
	v_or_b32_e32 v8, v8, v57
	v_lshl_add_u64 v[10:11], s[60:61], 0, v[8:9]
	v_lshl_add_u64 v[8:9], s[66:67], 0, v[8:9]
	global_load_ushort v12, v[10:11], off
	global_load_ushort v13, v[8:9], off
	v_or_b32_e32 v8, 14, v2
	v_ashrrev_i32_e32 v9, 31, v8
	v_or_b32_e32 v2, 15, v2
	v_lshlrev_b64 v[8:9], 10, v[8:9]
	v_ashrrev_i32_e32 v3, 31, v2
	v_or_b32_e32 v8, v8, v57
	v_lshlrev_b64 v[2:3], 10, v[2:3]
	v_lshl_add_u64 v[10:11], s[60:61], 0, v[8:9]
	v_lshl_add_u64 v[8:9], s[66:67], 0, v[8:9]
	v_or_b32_e32 v2, v2, v57
	global_load_ushort v10, v[10:11], off
	s_mov_b32 s2, 0x3d800000
	global_load_ushort v11, v[8:9], off
	v_lshl_add_u64 v[8:9], s[60:61], 0, v[2:3]
	v_lshl_add_u64 v[2:3], s[66:67], 0, v[2:3]
	global_load_ushort v8, v[8:9], off
	v_cmp_eq_u32_e64 s[4:5], 2, v7
	global_load_ushort v9, v[2:3], off
	v_lshl_add_u32 v2, v7, 10, 0
	v_add_u32_e32 v2, 0x1c800, v2
	s_waitcnt lgkmcnt(0)
	s_barrier
	ds_read_b128 v[58:61], v2
	ds_read_b128 v[62:65], v2 offset:16
	ds_read_b128 v[66:69], v2 offset:32
	ds_read_b128 v[70:73], v2 offset:48
	s_waitcnt vmcnt(47) lgkmcnt(3)
	v_mul_f32_e32 v3, v40, v59
	v_fmac_f32_e32 v3, v4, v58
	s_waitcnt vmcnt(43) lgkmcnt(2)
	v_mul_f32_e32 v57, v43, v63
	v_fmac_f32_e32 v3, v47, v60
	v_fmac_f32_e32 v57, v42, v62
	v_fmac_f32_e32 v3, v48, v61
	s_waitcnt vmcnt(42)
	v_fmac_f32_e32 v57, v44, v64
	s_waitcnt vmcnt(32)
	v_add_f32_e32 v3, v56, v3
	v_fmac_f32_e32 v57, v45, v65
	v_add_f32_e32 v3, v3, v57
	s_waitcnt lgkmcnt(1)
	v_mul_f32_e32 v57, v41, v67
	v_fmac_f32_e32 v57, v5, v66
	v_fmac_f32_e32 v57, v54, v68
	v_fmac_f32_e32 v57, v55, v69
	v_add_f32_e32 v3, v3, v57
	s_waitcnt lgkmcnt(0)
	v_mul_f32_e32 v57, v51, v71
	v_fmac_f32_e32 v57, v50, v70
	v_fmac_f32_e32 v57, v53, v72
	v_fmac_f32_e32 v57, v52, v73
	v_add_f32_e32 v3, v3, v57
	v_min_f32_e32 v57, 0, v3
	v_mul_f32_e64 v3, |v3|, s3
	v_exp_f32_e32 v3, v3
	ds_read_b128 v[58:61], v2 offset:64
	v_add_f32_e32 v3, 1.0, v3
	v_log_f32_e32 v3, v3
	s_nop 0
	v_fmac_f32_e32 v57, 0xbf317218, v3
	s_waitcnt lgkmcnt(0)
	v_mul_f32_e32 v3, v40, v59
	v_fmac_f32_e32 v3, v4, v58
	v_fmac_f32_e32 v3, v47, v60
	v_fmac_f32_e32 v3, v48, v61
	ds_read_b128 v[58:61], v2 offset:80
	v_add_f32_e32 v3, v56, v3
	v_fma_f32 v57, v57, s2, 0
	s_waitcnt lgkmcnt(0)
	v_mul_f32_e32 v59, v43, v59
	v_fmac_f32_e32 v59, v42, v58
	v_fmac_f32_e32 v59, v44, v60
	v_fmac_f32_e32 v59, v45, v61
	v_add_f32_e32 v3, v3, v59
	ds_read_b128 v[58:61], v2 offset:96
	s_waitcnt lgkmcnt(0)
	v_mul_f32_e32 v59, v41, v59
	v_fmac_f32_e32 v59, v5, v58
	v_fmac_f32_e32 v59, v54, v60
	v_fmac_f32_e32 v59, v55, v61
	v_add_f32_e32 v3, v3, v59
	ds_read_b128 v[58:61], v2 offset:112
	s_waitcnt lgkmcnt(0)
	v_mul_f32_e32 v59, v51, v59
	v_fmac_f32_e32 v59, v50, v58
	v_fmac_f32_e32 v59, v53, v60
	v_fmac_f32_e32 v59, v52, v61
	v_add_f32_e32 v3, v3, v59
	v_min_f32_e32 v58, 0, v3
	v_mul_f32_e64 v3, |v3|, s3
	v_exp_f32_e32 v3, v3
	ds_read_b128 v[60:63], v2 offset:128
	v_add_f32_e32 v3, 1.0, v3
	v_log_f32_e32 v3, v3
	s_nop 0
	v_fmac_f32_e32 v58, 0xbf317218, v3
	s_waitcnt lgkmcnt(0)
	v_mul_f32_e32 v3, v40, v61
	v_fmac_f32_e32 v3, v4, v60
	v_fmac_f32_e32 v3, v47, v62
	v_fmac_f32_e32 v3, v48, v63
	ds_read_b128 v[60:63], v2 offset:144
	v_add_f32_e32 v3, v56, v3
	v_fmamk_f32 v58, v58, 0x3d800000, v57
	s_waitcnt lgkmcnt(0)
	v_mul_f32_e32 v59, v43, v61
	v_fmac_f32_e32 v59, v42, v60
	v_fmac_f32_e32 v59, v44, v62
	v_fmac_f32_e32 v59, v45, v63
	ds_read_b128 v[60:63], v2 offset:160
	v_add_f32_e32 v3, v3, v59
	s_waitcnt lgkmcnt(0)
	v_mul_f32_e32 v59, v41, v61
	v_fmac_f32_e32 v59, v5, v60
	v_fmac_f32_e32 v59, v54, v62
	v_fmac_f32_e32 v59, v55, v63
	ds_read_b128 v[60:63], v2 offset:176
	v_add_f32_e32 v3, v3, v59
	s_waitcnt lgkmcnt(0)
; #define LAS __attribute__((address_space(3)))
; __device__ __forceinline__ float logsigmoidf_(float x) { return fminf(x, 0.f) - LN2 * flog2(1.f + fexp2(-fabsf(x) * LOG2E)); }
; __device__ __forceinline__ void gla_pre_unit(LAS unsigned char* lds, int b, int h, int ci, unsigned char* ws, const float* w_gate, const float* b_gate) {
;     ...
;     for (int tt = 0; tt < 16; ++tt) {
;         const int t = seg * 16 + tt; float x = bg;
; #pragma unroll
;         for (int j4 = 0; j4 < 4; ++j4) { const f32x4 a = *(const LAS f32x4*)(GAL + t * 16 + j4 * 4); x += a[0] * wg[j4 * 4] + a[1] * wg[j4 * 4 + 1] + a[2] * wg[j4 * 4 + 2] + a[3] * wg[j4 * 4 + 3]; }
;         run += logsigmoidf_(x) * (1.f / 16.f); bc[tt] = run;
;     }
	v_mul_f32_e32 v59, v51, v61
	v_fmac_f32_e32 v59, v50, v60
	v_fmac_f32_e32 v59, v53, v62
	v_fmac_f32_e32 v59, v52, v63
	v_add_f32_e32 v3, v3, v59
	v_min_f32_e32 v59, 0, v3
	v_mul_f32_e64 v3, |v3|, s3
	v_exp_f32_e32 v3, v3
	ds_read_b128 v[60:63], v2 offset:192
	v_add_f32_e32 v3, 1.0, v3
	v_log_f32_e32 v3, v3
	s_nop 0
	v_fmac_f32_e32 v59, 0xbf317218, v3
	s_waitcnt lgkmcnt(0)
	v_mul_f32_e32 v3, v40, v61
	v_fmac_f32_e32 v3, v4, v60
	v_fmac_f32_e32 v3, v47, v62
	v_fmac_f32_e32 v3, v48, v63
	ds_read_b128 v[60:63], v2 offset:208
	v_add_f32_e32 v3, v56, v3
	v_fmamk_f32 v59, v59, 0x3d800000, v58
	s_waitcnt lgkmcnt(0)
	v_mul_f32_e32 v61, v43, v61
	v_fmac_f32_e32 v61, v42, v60
	v_fmac_f32_e32 v61, v44, v62
	v_fmac_f32_e32 v61, v45, v63
	v_add_f32_e32 v3, v3, v61
	ds_read_b128 v[60:63], v2 offset:224
	s_waitcnt lgkmcnt(0)
	v_mul_f32_e32 v61, v41, v61
	v_fmac_f32_e32 v61, v5, v60
	v_fmac_f32_e32 v61, v54, v62
	v_fmac_f32_e32 v61, v55, v63
	v_add_f32_e32 v3, v3, v61
	ds_read_b128 v[60:63], v2 offset:240
	s_waitcnt lgkmcnt(0)
	v_mul_f32_e32 v61, v51, v61
	v_fmac_f32_e32 v61, v50, v60
	v_fmac_f32_e32 v61, v53, v62
	v_fmac_f32_e32 v61, v52, v63
	v_add_f32_e32 v3, v3, v61
	v_min_f32_e32 v60, 0, v3
	v_mul_f32_e64 v3, |v3|, s3
	v_exp_f32_e32 v3, v3
	ds_read_b128 v[62:65], v2 offset:256
	v_add_f32_e32 v3, 1.0, v3
	v_log_f32_e32 v3, v3
	s_nop 0
	v_fmac_f32_e32 v60, 0xbf317218, v3
	s_waitcnt lgkmcnt(0)
	v_mul_f32_e32 v3, v40, v63
	v_fmac_f32_e32 v3, v4, v62
	v_fmac_f32_e32 v3, v47, v64
	v_fmac_f32_e32 v3, v48, v65
	ds_read_b128 v[62:65], v2 offset:272
	v_add_f32_e32 v3, v56, v3
	v_fmamk_f32 v60, v60, 0x3d800000, v59
	s_waitcnt lgkmcnt(0)
	v_mul_f32_e32 v61, v43, v63
	v_fmac_f32_e32 v61, v42, v62
	v_fmac_f32_e32 v61, v44, v64
	v_fmac_f32_e32 v61, v45, v65
	ds_read_b128 v[62:65], v2 offset:288
	v_add_f32_e32 v3, v3, v61
	s_waitcnt lgkmcnt(0)
	v_mul_f32_e32 v61, v41, v63
	v_fmac_f32_e32 v61, v5, v62
	v_fmac_f32_e32 v61, v54, v64
	v_fmac_f32_e32 v61, v55, v65
	ds_read_b128 v[62:65], v2 offset:304
	v_add_f32_e32 v3, v3, v61
	s_waitcnt lgkmcnt(0)
	v_mul_f32_e32 v61, v51, v63
	v_fmac_f32_e32 v61, v50, v62
	v_fmac_f32_e32 v61, v53, v64
	v_fmac_f32_e32 v61, v52, v65
	v_add_f32_e32 v3, v3, v61
	v_min_f32_e32 v61, 0, v3
	v_mul_f32_e64 v3, |v3|, s3
	v_exp_f32_e32 v3, v3
	ds_read_b128 v[62:65], v2 offset:320
	v_add_f32_e32 v3, 1.0, v3
	v_log_f32_e32 v3, v3
	s_nop 0
	v_fmac_f32_e32 v61, 0xbf317218, v3
	s_waitcnt lgkmcnt(0)
	v_mul_f32_e32 v3, v40, v63
	v_fmac_f32_e32 v3, v4, v62
	v_fmac_f32_e32 v3, v47, v64
	v_fmac_f32_e32 v3, v48, v65
	ds_read_b128 v[62:65], v2 offset:336
	v_add_f32_e32 v3, v56, v3
	v_fmamk_f32 v61, v61, 0x3d800000, v60
	s_waitcnt lgkmcnt(0)
	v_mul_f32_e32 v63, v43, v63
	v_fmac_f32_e32 v63, v42, v62
	v_fmac_f32_e32 v63, v44, v64
	v_fmac_f32_e32 v63, v45, v65
	v_add_f32_e32 v3, v3, v63
	ds_read_b128 v[62:65], v2 offset:352
	s_waitcnt lgkmcnt(0)
	v_mul_f32_e32 v63, v41, v63
	v_fmac_f32_e32 v63, v5, v62
	v_fmac_f32_e32 v63, v54, v64
	v_fmac_f32_e32 v63, v55, v65
	v_add_f32_e32 v3, v3, v63
	ds_read_b128 v[62:65], v2 offset:368
	s_waitcnt lgkmcnt(0)
	v_mul_f32_e32 v63, v51, v63
	v_fmac_f32_e32 v63, v50, v62
	v_fmac_f32_e32 v63, v53, v64
	v_fmac_f32_e32 v63, v52, v65
	v_add_f32_e32 v3, v3, v63
	v_min_f32_e32 v62, 0, v3
	v_mul_f32_e64 v3, |v3|, s3
	v_exp_f32_e32 v3, v3
	ds_read_b128 v[64:67], v2 offset:384
	v_add_f32_e32 v3, 1.0, v3
	v_log_f32_e32 v3, v3
	s_nop 0
	v_fmac_f32_e32 v62, 0xbf317218, v3
	s_waitcnt lgkmcnt(0)
	v_mul_f32_e32 v3, v40, v65
	v_fmac_f32_e32 v3, v4, v64
	v_fmac_f32_e32 v3, v47, v66
	v_fmac_f32_e32 v3, v48, v67
	ds_read_b128 v[64:67], v2 offset:400
	v_add_f32_e32 v3, v56, v3
	v_fmamk_f32 v62, v62, 0x3d800000, v61
	s_waitcnt lgkmcnt(0)
	v_mul_f32_e32 v63, v43, v65
	v_fmac_f32_e32 v63, v42, v64
	v_fmac_f32_e32 v63, v44, v66
	v_fmac_f32_e32 v63, v45, v67
	ds_read_b128 v[64:67], v2 offset:416
	v_add_f32_e32 v3, v3, v63
	s_waitcnt lgkmcnt(0)
	v_mul_f32_e32 v63, v41, v65
	v_fmac_f32_e32 v63, v5, v64
	v_fmac_f32_e32 v63, v54, v66
	v_fmac_f32_e32 v63, v55, v67
	ds_read_b128 v[64:67], v2 offset:432
	v_add_f32_e32 v3, v3, v63
	s_waitcnt lgkmcnt(0)
	v_mul_f32_e32 v63, v51, v65
	v_fmac_f32_e32 v63, v50, v64
	v_fmac_f32_e32 v63, v53, v66
	v_fmac_f32_e32 v63, v52, v67
	v_add_f32_e32 v3, v3, v63
	v_min_f32_e32 v63, 0, v3
	v_mul_f32_e64 v3, |v3|, s3
	v_exp_f32_e32 v3, v3
	ds_read_b128 v[64:67], v2 offset:448
	v_add_f32_e32 v3, 1.0, v3
	v_log_f32_e32 v3, v3
	s_nop 0
	v_fmac_f32_e32 v63, 0xbf317218, v3
	s_waitcnt lgkmcnt(0)
	v_mul_f32_e32 v3, v40, v65
	v_fmac_f32_e32 v3, v4, v64
	v_fmac_f32_e32 v3, v47, v66
	v_fmac_f32_e32 v3, v48, v67
	ds_read_b128 v[64:67], v2 offset:464
	v_add_f32_e32 v3, v56, v3
	v_fmamk_f32 v63, v63, 0x3d800000, v62
	s_waitcnt lgkmcnt(0)
	v_mul_f32_e32 v65, v43, v65
	v_fmac_f32_e32 v65, v42, v64
	v_fmac_f32_e32 v65, v44, v66
	v_fmac_f32_e32 v65, v45, v67
	v_add_f32_e32 v3, v3, v65
	ds_read_b128 v[64:67], v2 offset:480
	s_waitcnt lgkmcnt(0)
	v_mul_f32_e32 v65, v41, v65
	v_fmac_f32_e32 v65, v5, v64
	v_fmac_f32_e32 v65, v54, v66
	v_fmac_f32_e32 v65, v55, v67
	v_add_f32_e32 v3, v3, v65
	ds_read_b128 v[64:67], v2 offset:496
	s_waitcnt lgkmcnt(0)
	v_mul_f32_e32 v65, v51, v65
	v_fmac_f32_e32 v65, v50, v64
	v_fmac_f32_e32 v65, v53, v66
	v_fmac_f32_e32 v65, v52, v67
	v_add_f32_e32 v3, v3, v65
	v_min_f32_e32 v64, 0, v3
	v_mul_f32_e64 v3, |v3|, s3
	v_exp_f32_e32 v3, v3
	ds_read_b128 v[66:69], v2 offset:512
	v_add_f32_e32 v3, 1.0, v3
	v_log_f32_e32 v3, v3
	s_nop 0
	v_fmac_f32_e32 v64, 0xbf317218, v3
	s_waitcnt lgkmcnt(0)
	v_mul_f32_e32 v3, v40, v67
	v_fmac_f32_e32 v3, v4, v66
	v_fmac_f32_e32 v3, v47, v68
	v_fmac_f32_e32 v3, v48, v69
	ds_read_b128 v[66:69], v2 offset:528
	v_add_f32_e32 v3, v56, v3
	v_fmamk_f32 v64, v64, 0x3d800000, v63
	s_waitcnt lgkmcnt(0)
; #define LAS __attribute__((address_space(3)))
; __device__ __forceinline__ float logsigmoidf_(float x) { return fminf(x, 0.f) - LN2 * flog2(1.f + fexp2(-fabsf(x) * LOG2E)); }
; __device__ __forceinline__ void gla_pre_unit(LAS unsigned char* lds, int b, int h, int ci, unsigned char* ws, const float* w_gate, const float* b_gate) {
;     ...
;     for (int tt = 0; tt < 16; ++tt) {
;         const int t = seg * 16 + tt; float x = bg;
; #pragma unroll
;         for (int j4 = 0; j4 < 4; ++j4) { const f32x4 a = *(const LAS f32x4*)(GAL + t * 16 + j4 * 4); x += a[0] * wg[j4 * 4] + a[1] * wg[j4 * 4 + 1] + a[2] * wg[j4 * 4 + 2] + a[3] * wg[j4 * 4 + 3]; }
;         run += logsigmoidf_(x) * (1.f / 16.f); bc[tt] = run;
;     }
	v_mul_f32_e32 v65, v43, v67
	v_fmac_f32_e32 v65, v42, v66
	v_fmac_f32_e32 v65, v44, v68
	v_fmac_f32_e32 v65, v45, v69
	ds_read_b128 v[66:69], v2 offset:544
	v_add_f32_e32 v3, v3, v65
	s_waitcnt lgkmcnt(0)
	v_mul_f32_e32 v65, v41, v67
	v_fmac_f32_e32 v65, v5, v66
	v_fmac_f32_e32 v65, v54, v68
	v_fmac_f32_e32 v65, v55, v69
	ds_read_b128 v[66:69], v2 offset:560
	v_add_f32_e32 v3, v3, v65
	s_waitcnt lgkmcnt(0)
	v_mul_f32_e32 v65, v51, v67
	v_fmac_f32_e32 v65, v50, v66
	v_fmac_f32_e32 v65, v53, v68
	v_fmac_f32_e32 v65, v52, v69
	v_add_f32_e32 v3, v3, v65
	v_min_f32_e32 v65, 0, v3
	v_mul_f32_e64 v3, |v3|, s3
	v_exp_f32_e32 v3, v3
	ds_read_b128 v[66:69], v2 offset:576
	v_add_f32_e32 v3, 1.0, v3
	v_log_f32_e32 v3, v3
	s_nop 0
	v_fmac_f32_e32 v65, 0xbf317218, v3
	s_waitcnt lgkmcnt(0)
	v_mul_f32_e32 v3, v40, v67
	v_fmac_f32_e32 v3, v4, v66
	v_fmac_f32_e32 v3, v47, v68
	v_fmac_f32_e32 v3, v48, v69
	ds_read_b128 v[66:69], v2 offset:592
	v_add_f32_e32 v3, v56, v3
	v_fmamk_f32 v65, v65, 0x3d800000, v64
	s_waitcnt lgkmcnt(0)
	v_mul_f32_e32 v67, v43, v67
	v_fmac_f32_e32 v67, v42, v66
	v_fmac_f32_e32 v67, v44, v68
	v_fmac_f32_e32 v67, v45, v69
	v_add_f32_e32 v3, v3, v67
	ds_read_b128 v[66:69], v2 offset:608
	s_waitcnt lgkmcnt(0)
	v_mul_f32_e32 v67, v41, v67
	v_fmac_f32_e32 v67, v5, v66
	v_fmac_f32_e32 v67, v54, v68
	v_fmac_f32_e32 v67, v55, v69
	v_add_f32_e32 v3, v3, v67
	ds_read_b128 v[66:69], v2 offset:624
	s_waitcnt lgkmcnt(0)
	v_mul_f32_e32 v67, v51, v67
	v_fmac_f32_e32 v67, v50, v66
	v_fmac_f32_e32 v67, v53, v68
	v_fmac_f32_e32 v67, v52, v69
	v_add_f32_e32 v3, v3, v67
	v_min_f32_e32 v66, 0, v3
	v_mul_f32_e64 v3, |v3|, s3
	v_exp_f32_e32 v3, v3
	ds_read_b128 v[68:71], v2 offset:640
	v_add_f32_e32 v3, 1.0, v3
	v_log_f32_e32 v3, v3
	s_nop 0
	v_fmac_f32_e32 v66, 0xbf317218, v3
	s_waitcnt lgkmcnt(0)
	v_mul_f32_e32 v3, v40, v69
	v_fmac_f32_e32 v3, v4, v68
	v_fmac_f32_e32 v3, v47, v70
	v_fmac_f32_e32 v3, v48, v71
	ds_read_b128 v[68:71], v2 offset:656
	v_add_f32_e32 v3, v56, v3
	v_fmamk_f32 v66, v66, 0x3d800000, v65
	s_waitcnt lgkmcnt(0)
	v_mul_f32_e32 v67, v43, v69
	v_fmac_f32_e32 v67, v42, v68
	v_fmac_f32_e32 v67, v44, v70
	v_fmac_f32_e32 v67, v45, v71
	ds_read_b128 v[68:71], v2 offset:672
	v_add_f32_e32 v3, v3, v67
	s_waitcnt lgkmcnt(0)
	v_mul_f32_e32 v67, v41, v69
	v_fmac_f32_e32 v67, v5, v68
	v_fmac_f32_e32 v67, v54, v70
	v_fmac_f32_e32 v67, v55, v71
	ds_read_b128 v[68:71], v2 offset:688
	v_add_f32_e32 v3, v3, v67
	s_waitcnt lgkmcnt(0)
	v_mul_f32_e32 v67, v51, v69
	v_fmac_f32_e32 v67, v50, v68
	v_fmac_f32_e32 v67, v53, v70
	v_fmac_f32_e32 v67, v52, v71
	v_add_f32_e32 v3, v3, v67
	v_min_f32_e32 v67, 0, v3
	v_mul_f32_e64 v3, |v3|, s3
	v_exp_f32_e32 v3, v3
	ds_read_b128 v[68:71], v2 offset:704
	v_add_f32_e32 v3, 1.0, v3
	v_log_f32_e32 v3, v3
	s_nop 0
	v_fmac_f32_e32 v67, 0xbf317218, v3
	s_waitcnt lgkmcnt(0)
	v_mul_f32_e32 v3, v40, v69
	v_fmac_f32_e32 v3, v4, v68
	v_fmac_f32_e32 v3, v47, v70
	v_fmac_f32_e32 v3, v48, v71
	ds_read_b128 v[68:71], v2 offset:720
	v_add_f32_e32 v3, v56, v3
	v_fmamk_f32 v67, v67, 0x3d800000, v66
	s_waitcnt lgkmcnt(0)
	v_mul_f32_e32 v69, v43, v69
	v_fmac_f32_e32 v69, v42, v68
	v_fmac_f32_e32 v69, v44, v70
	v_fmac_f32_e32 v69, v45, v71
	v_add_f32_e32 v3, v3, v69
	ds_read_b128 v[68:71], v2 offset:736
	s_waitcnt lgkmcnt(0)
	v_mul_f32_e32 v69, v41, v69
	v_fmac_f32_e32 v69, v5, v68
	v_fmac_f32_e32 v69, v54, v70
	v_fmac_f32_e32 v69, v55, v71
	v_add_f32_e32 v3, v3, v69
	ds_read_b128 v[68:71], v2 offset:752
	s_waitcnt lgkmcnt(0)
	v_mul_f32_e32 v69, v51, v69
	v_fmac_f32_e32 v69, v50, v68
	v_fmac_f32_e32 v69, v53, v70
	v_fmac_f32_e32 v69, v52, v71
	v_add_f32_e32 v3, v3, v69
	v_min_f32_e32 v68, 0, v3
	v_mul_f32_e64 v3, |v3|, s3
	v_exp_f32_e32 v3, v3
	ds_read_b128 v[70:73], v2 offset:768
	v_add_f32_e32 v3, 1.0, v3
	v_log_f32_e32 v3, v3
	s_nop 0
	v_fmac_f32_e32 v68, 0xbf317218, v3
	s_waitcnt lgkmcnt(0)
	v_mul_f32_e32 v3, v40, v71
	v_fmac_f32_e32 v3, v4, v70
	v_fmac_f32_e32 v3, v47, v72
	v_fmac_f32_e32 v3, v48, v73
	ds_read_b128 v[70:73], v2 offset:784
	v_add_f32_e32 v3, v56, v3
	v_fmamk_f32 v68, v68, 0x3d800000, v67
	s_waitcnt lgkmcnt(0)
	v_mul_f32_e32 v69, v43, v71
	v_fmac_f32_e32 v69, v42, v70
	v_fmac_f32_e32 v69, v44, v72
	v_fmac_f32_e32 v69, v45, v73
	ds_read_b128 v[70:73], v2 offset:800
	v_add_f32_e32 v3, v3, v69
	s_waitcnt lgkmcnt(0)
; #define LAS __attribute__((address_space(3)))
; __device__ __forceinline__ float fexp2(float x) { return __builtin_amdgcn_exp2f(x); }
; __device__ __forceinline__ float logsigmoidf_(float x) { return fminf(x, 0.f) - LN2 * flog2(1.f + fexp2(-fabsf(x) * LOG2E)); }
; __device__ __forceinline__ void gla_pre_unit(LAS unsigned char* lds, int b, int h, int ci, unsigned char* ws, const float* w_gate, const float* b_gate) {
;     ...
;     for (int tt = 0; tt < 16; ++tt) {
;         const int t = seg * 16 + tt; float x = bg;
; #pragma unroll
;         for (int j4 = 0; j4 < 4; ++j4) { const f32x4 a = *(const LAS f32x4*)(GAL + t * 16 + j4 * 4); x += a[0] * wg[j4 * 4] + a[1] * wg[j4 * 4 + 1] + a[2] * wg[j4 * 4 + 2] + a[3] * wg[j4 * 4 + 3]; }
;         run += logsigmoidf_(x) * (1.f / 16.f); bc[tt] = run;
;     }
;     SEGTOT[seg * 128 + c] = run; if (seg == 2) BFIRST[c] = bc[0];
;     __syncthreads();
;     {
;         const float s0 = SEGTOT[c], s1 = SEGTOT[128 + c], s2 = SEGTOT[256 + c], s3 = SEGTOT[384 + c];
;         const float offs = (seg == 0) ? 0.f : (seg == 1) ? s0 : (seg == 2) ? (s0 + s1) : (s0 + s1 + s2);
;         const float blast = s0 + s1 + s2 + s3, bref = s0 + s1 + BFIRST[c];
;         if (seg == 0) DECAY[c] = fexp2(blast * LOG2E);
	v_mul_f32_e32 v69, v41, v71
	v_fmac_f32_e32 v69, v5, v70
	v_fmac_f32_e32 v69, v54, v72
	v_fmac_f32_e32 v69, v55, v73
	ds_read_b128 v[70:73], v2 offset:816
	v_add_f32_e32 v3, v3, v69
	s_waitcnt lgkmcnt(0)
	v_mul_f32_e32 v69, v51, v71
	v_fmac_f32_e32 v69, v50, v70
	v_fmac_f32_e32 v69, v53, v72
	v_fmac_f32_e32 v69, v52, v73
	v_add_f32_e32 v3, v3, v69
	v_min_f32_e32 v69, 0, v3
	v_mul_f32_e64 v3, |v3|, s3
	v_exp_f32_e32 v3, v3
	ds_read_b128 v[70:73], v2 offset:832
	v_add_f32_e32 v3, 1.0, v3
	v_log_f32_e32 v3, v3
	s_nop 0
	v_fmac_f32_e32 v69, 0xbf317218, v3
	s_waitcnt lgkmcnt(0)
	v_mul_f32_e32 v3, v40, v71
	v_fmac_f32_e32 v3, v4, v70
	v_fmac_f32_e32 v3, v47, v72
	v_fmac_f32_e32 v3, v48, v73
	ds_read_b128 v[70:73], v2 offset:848
	v_add_f32_e32 v3, v56, v3
	v_fmamk_f32 v69, v69, 0x3d800000, v68
	s_waitcnt lgkmcnt(0)
	v_mul_f32_e32 v71, v43, v71
	v_fmac_f32_e32 v71, v42, v70
	v_fmac_f32_e32 v71, v44, v72
	v_fmac_f32_e32 v71, v45, v73
	v_add_f32_e32 v3, v3, v71
	ds_read_b128 v[70:73], v2 offset:864
	s_waitcnt lgkmcnt(0)
	v_mul_f32_e32 v71, v41, v71
	v_fmac_f32_e32 v71, v5, v70
	v_fmac_f32_e32 v71, v54, v72
	v_fmac_f32_e32 v71, v55, v73
	v_add_f32_e32 v3, v3, v71
	ds_read_b128 v[70:73], v2 offset:880
	s_waitcnt lgkmcnt(0)
	v_mul_f32_e32 v71, v51, v71
	v_fmac_f32_e32 v71, v50, v70
	v_fmac_f32_e32 v71, v53, v72
	v_fmac_f32_e32 v71, v52, v73
	v_add_f32_e32 v3, v3, v71
	v_min_f32_e32 v70, 0, v3
	v_mul_f32_e64 v3, |v3|, s3
	v_exp_f32_e32 v3, v3
	ds_read_b128 v[72:75], v2 offset:896
	v_add_f32_e32 v3, 1.0, v3
	v_log_f32_e32 v3, v3
	s_nop 0
	v_fmac_f32_e32 v70, 0xbf317218, v3
	s_waitcnt lgkmcnt(0)
	v_mul_f32_e32 v3, v40, v73
	v_fmac_f32_e32 v3, v4, v72
	v_fmac_f32_e32 v3, v47, v74
	v_fmac_f32_e32 v3, v48, v75
	ds_read_b128 v[72:75], v2 offset:912
	v_add_f32_e32 v3, v56, v3
	v_fmamk_f32 v70, v70, 0x3d800000, v69
	s_waitcnt lgkmcnt(0)
	v_mul_f32_e32 v71, v43, v73
	v_fmac_f32_e32 v71, v42, v72
	v_fmac_f32_e32 v71, v44, v74
	v_fmac_f32_e32 v71, v45, v75
	ds_read_b128 v[72:75], v2 offset:928
	v_add_f32_e32 v3, v3, v71
	s_waitcnt lgkmcnt(0)
	v_mul_f32_e32 v71, v41, v73
	v_fmac_f32_e32 v71, v5, v72
	v_fmac_f32_e32 v71, v54, v74
	v_fmac_f32_e32 v71, v55, v75
	ds_read_b128 v[72:75], v2 offset:944
	v_add_f32_e32 v3, v3, v71
	s_waitcnt lgkmcnt(0)
	v_mul_f32_e32 v71, v51, v73
	v_fmac_f32_e32 v71, v50, v72
	v_fmac_f32_e32 v71, v53, v74
	v_fmac_f32_e32 v71, v52, v75
	v_add_f32_e32 v3, v3, v71
	v_min_f32_e32 v71, 0, v3
	v_mul_f32_e64 v3, |v3|, s3
	v_exp_f32_e32 v3, v3
	ds_read_b128 v[72:75], v2 offset:960
	v_add_f32_e32 v3, 1.0, v3
	v_log_f32_e32 v3, v3
	s_nop 0
	v_fmac_f32_e32 v71, 0xbf317218, v3
	s_waitcnt lgkmcnt(0)
	v_mul_f32_e32 v3, v40, v73
	v_fmac_f32_e32 v3, v4, v72
	v_fmac_f32_e32 v3, v47, v74
	v_fmac_f32_e32 v3, v48, v75
	ds_read_b128 v[72:75], v2 offset:976
	v_add_f32_e32 v3, v56, v3
	v_fmamk_f32 v71, v71, 0x3d800000, v70
	s_waitcnt lgkmcnt(0)
	v_mul_f32_e32 v4, v43, v73
	v_fmac_f32_e32 v4, v42, v72
	v_fmac_f32_e32 v4, v44, v74
	v_fmac_f32_e32 v4, v45, v75
	ds_read_b128 v[42:45], v2 offset:992
	v_add_f32_e32 v3, v3, v4
	s_waitcnt lgkmcnt(0)
	v_mul_f32_e32 v4, v41, v43
	v_fmac_f32_e32 v4, v5, v42
	v_fmac_f32_e32 v4, v54, v44
	v_fmac_f32_e32 v4, v55, v45
	v_add_f32_e32 v40, v3, v4
	ds_read_b128 v[2:5], v2 offset:1008
	v_lshl_add_u32 v41, v0, 2, 0
	s_waitcnt lgkmcnt(0)
	v_mul_f32_e32 v3, v51, v3
	v_fmac_f32_e32 v3, v50, v2
	v_fmac_f32_e32 v3, v53, v4
	v_fmac_f32_e32 v3, v52, v5
	v_add_f32_e32 v2, v40, v3
	v_min_f32_e32 v3, 0, v2
	v_mul_f32_e64 v2, |v2|, s3
	v_exp_f32_e32 v2, v2
	v_lshl_add_u32 v40, v6, 2, 0
	v_add_f32_e32 v2, 1.0, v2
	v_log_f32_e32 v2, v2
	s_nop 0
	v_fmac_f32_e32 v3, 0xbf317218, v2
	v_fmamk_f32 v43, v3, 0x3d800000, v71
	v_add_u32_e32 v2, 0x1d800, v40
	ds_write_b32 v2, v43
	s_and_saveexec_b64 s[2:3], s[4:5]
	v_add_u32_e32 v2, 0x1e000, v41
	ds_write_b32 v2, v57
	s_or_b64 exec, exec, s[2:3]
	v_add_u32_e32 v2, 0x1d800, v41
	s_waitcnt lgkmcnt(0)
	s_barrier
	ds_read2st64_b32 v[4:5], v2 offset1:2
	ds_read2st64_b32 v[2:3], v2 offset0:4 offset1:6
	s_movk_i32 s2, 0x80
	v_cmp_gt_u32_e32 vcc, s2, v6
	s_movk_i32 s2, 0x7f
	v_cmp_lt_u32_e64 s[6:7], s2, v6
	s_waitcnt lgkmcnt(1)
	v_add_f32_e32 v42, v4, v5
	s_and_saveexec_b64 s[2:3], s[6:7]
	s_xor_b64 s[2:3], exec, s[2:3]
	s_cbranch_execz .LBB0_327
	v_add_f32_e32 v42, v4, v5
	s_waitcnt lgkmcnt(0)
	v_add_f32_e32 v45, v42, v2
	v_cndmask_b32_e64 v5, v45, v42, s[4:5]
	v_cmp_eq_u32_e64 s[4:5], 1, v7
	s_nop 1
	v_cndmask_b32_e64 v44, v5, v4, s[4:5]
